# gate/up epilogue rewritten by hand: packed f32 SwiGLU (v_pk_mul/v_pk_add, 4 pairs interleaved, no hazard nops), saddr stores; gelu-branch rinv loads hoisted
# speedup vs baseline: 1.0203x; 1.0100x over previous
; __device__ __forceinline__ unsigned pkbf(float lo, float hi) { unsigned r; asm("v_cvt_pk_bf16_f32 %0, %1, %2" : "=v"(r) : "v"(lo), "v"(hi)); return r; }
; __device__ __forceinline__ f32x2 gelu_pk(f32x2 v) {
;     const f32x2 av = __builtin_elementwise_abs(v), d = av * 0.2316418882f + 1.0f;
;     f32x2 t; t.x = __builtin_amdgcn_rcpf(d.x); t.y = __builtin_amdgcn_rcpf(d.y);
;     f32x2 q = t * 0.5307027145f + (-0.7265760135f); q = q * t + 0.7107068705f; q = q * t + (-0.142248368f); q = q * t + 0.127414796f; q = q * t;
;     const f32x2 s = (v * v) * (-0.72134752044f);
;     f32x2 e; e.x = __builtin_amdgcn_exp2f(s.x); e.y = __builtin_amdgcn_exp2f(s.y);
;     const f32x2 m = v * (q * e), r = v - m;
;     f32x2 o; o.x = v.x < 0.f ? m.x : r.x; o.y = v.y < 0.f ? m.y : r.y; return o;
; }
;     __device__ __forceinline__ void operator()(const f32x4 (&acc)[2][2][4][2], const Unit& u, int wr, int wc, int fr, int fq) const {
;         const int sec = u.pn >> 1, half = u.pn & 1;
;         const int row0 = u.pm * BM + wr * 64 + fr;
;         if (sec < 2) {
;             bf16_t* base = (sec == 0 ? U : VG) + half * 256 + wc * 32 + 8 * fq;
; #pragma unroll
;             for (int ai = 0; ai < 2; ++ai)
; #pragma unroll
;                 for (int m = 0; m < 4; ++m) { const int row = row0 + ai * HALF + m * 16; const float rs = rinv[row]; bf16_t* rowp = base + (size_t)row * 512;
; #pragma unroll
;                     for (int bj = 0; bj < 2; ++bj) { f32x4 v0 = acc[ai][bj][m][0] * rs, v1 = acc[ai][bj][m][1] * rs;
;                         f32x2 a = gelu_pk((f32x2){v0[0], v0[1]}), b = gelu_pk((f32x2){v0[2], v0[3]}), c = gelu_pk((f32x2){v1[0], v1[1]}), d = gelu_pk((f32x2){v1[2], v1[3]});
;                         u32x4 w; w.x = pkbf(a.x, a.y); w.y = pkbf(b.x, b.y); w.z = pkbf(c.x, c.y); w.w = pkbf(d.x, d.y);
;                         *(u32x4*)(rowp + bj * HALF) = w; } }
.LBB0_150:
	v_ashrrev_i32_e32 v159, 31, v158
	v_lshl_add_u64 v[130:131], v[158:159], 2, s[40:41]
	global_load_dword v166, v[130:131], off
	global_load_dword v168, v[130:131], off offset:64
	global_load_dword v170, v[130:131], off offset:128
	global_load_dword v172, v[130:131], off offset:192
	global_load_dword v174, v[130:131], off offset:512
	global_load_dword v176, v[130:131], off offset:576
	global_load_dword v178, v[130:131], off offset:640
	global_load_dword v180, v[130:131], off offset:704
	s_cmp_lt_u32 s44, 2
	s_mov_b32 s10, 0xb800000
	s_cselect_b32 s10, s10, 0xd800000
	s_add_u32 s10, s2, s10
	s_addc_u32 s11, s3, 0
	s_lshl_b32 s26, s45, 1
	s_add_u32 s10, s10, s26
	s_addc_u32 s11, s11, 0
	s_add_u32 s10, s10, s7
	s_addc_u32 s11, s11, 0
	v_lshlrev_b32_e32 v192, 1, v152
	v_lshl_add_u64 v[132:133], s[10:11], 0, v[192:193]
	s_mov_b32 s10, 0xbf3a00e3
	v_lshlrev_b64 v[128:129], 10, v[158:159]
	v_lshl_add_u64 v[128:129], v[132:133], 0, v[128:129]
	s_mov_b64 s[82:83], 0x28000
	s_waitcnt vmcnt(0) lgkmcnt(0)
	v_pk_mul_f32 v[124:125], v[124:125], v[166:167] op_sel_hi:[1,0]
	v_pk_mul_f32 v[136:137], v[120:121], v[166:167] op_sel_hi:[1,0]
	v_and_b32_e32 v121, 0x7fffffff, v125
	v_and_b32_e32 v120, 0x7fffffff, v124
	v_pk_fma_f32 v[120:121], v[120:121], s[36:37], 1.0 op_sel_hi:[1,0,0]
	v_pk_mul_f32 v[142:143], v[124:125], v[124:125]
	v_rcp_f32_e32 v138, v120
	v_rcp_f32_e32 v139, v121
	v_mov_b64_e32 v[120:121], s[10:11]
	v_pk_mul_f32 v[142:143], v[142:143], s[58:59] op_sel_hi:[1,0]
	v_pk_mul_f32 v[126:127], v[126:127], v[166:167] op_sel_hi:[1,0]
	v_pk_fma_f32 v[140:141], v[138:139], s[12:13], v[120:121] op_sel_hi:[1,0,0]
	v_exp_f32_e32 v142, v142
	v_pk_fma_f32 v[140:141], v[138:139], v[140:141], s[8:9] op_sel_hi:[1,1,0]
	v_exp_f32_e32 v143, v143
	v_pk_fma_f32 v[140:141], v[138:139], v[140:141], s[24:25] op_sel_hi:[1,1,0]
	v_cmp_gt_f32_e32 vcc, 0, v124
	v_pk_fma_f32 v[140:141], v[138:139], v[140:141], s[56:57] op_sel_hi:[1,1,0]
	v_pk_mul_f32 v[122:123], v[122:123], v[166:167] op_sel_hi:[1,0]
	v_pk_mul_f32 v[138:139], v[138:139], v[140:141]
	v_pk_mul_f32 v[140:141], v[126:127], v[126:127]
	v_pk_mul_f32 v[138:139], v[142:143], v[138:139]
	s_mov_b32 s10, 0x20000
	v_pk_mul_f32 v[142:143], v[124:125], v[138:139]
	v_pk_fma_f32 v[138:139], v[124:125], v[138:139], v[124:125] neg_lo:[1,0,0] neg_hi:[1,0,0]
	v_and_b32_e32 v124, 0x7fffffff, v126
	v_cndmask_b32_e32 v135, v138, v142, vcc
	v_cmp_gt_f32_e32 vcc, 0, v125
	v_and_b32_e32 v125, 0x7fffffff, v127
	v_pk_fma_f32 v[124:125], v[124:125], s[36:37], 1.0 op_sel_hi:[1,0,0]
	v_cndmask_b32_e32 v142, v139, v143, vcc
	v_rcp_f32_e32 v124, v124
	v_rcp_f32_e32 v125, v125
	v_cmp_gt_f32_e32 vcc, 0, v126
	v_pk_mul_f32 v[116:117], v[116:117], v[166:167] op_sel_hi:[1,0]
	v_pk_mul_f32 v[118:119], v[118:119], v[166:167] op_sel_hi:[1,0]
	v_pk_fma_f32 v[138:139], v[124:125], s[12:13], v[120:121] op_sel_hi:[1,0,0]
	v_pk_mul_f32 v[112:113], v[112:113], v[166:167] op_sel_hi:[1,0]
	v_pk_fma_f32 v[138:139], v[124:125], v[138:139], s[8:9] op_sel_hi:[1,1,0]
	v_pk_mul_f32 v[114:115], v[114:115], v[166:167] op_sel_hi:[1,0]
	v_pk_fma_f32 v[138:139], v[124:125], v[138:139], s[24:25] op_sel_hi:[1,1,0]
	s_nop 0
	v_pk_fma_f32 v[138:139], v[124:125], v[138:139], s[56:57] op_sel_hi:[1,1,0]
	s_nop 0
	v_pk_mul_f32 v[124:125], v[124:125], v[138:139]
	v_pk_mul_f32 v[138:139], v[140:141], s[58:59] op_sel_hi:[1,0]
	s_nop 0
	v_exp_f32_e32 v138, v138
	v_exp_f32_e32 v139, v139
	s_nop 0
	v_pk_mul_f32 v[124:125], v[138:139], v[124:125]
	s_nop 0
	v_pk_mul_f32 v[138:139], v[126:127], v[124:125]
	v_pk_fma_f32 v[124:125], v[126:127], v[124:125], v[126:127] neg_lo:[1,0,0] neg_hi:[1,0,0]
	s_nop 0
	v_cndmask_b32_e32 v140, v124, v138, vcc
	v_cmp_gt_f32_e32 vcc, 0, v127
	v_and_b32_e32 v124, 0x7fffffff, v136
	s_nop 0
	v_cndmask_b32_e32 v141, v125, v139, vcc
	v_and_b32_e32 v125, 0x7fffffff, v137
	v_pk_fma_f32 v[124:125], v[124:125], s[36:37], 1.0 op_sel_hi:[1,0,0]
	v_pk_mul_f32 v[138:139], v[136:137], v[136:137]
	v_rcp_f32_e32 v124, v124
	v_rcp_f32_e32 v125, v125
	v_pk_mul_f32 v[138:139], v[138:139], s[58:59] op_sel_hi:[1,0]
	v_cmp_gt_f32_e32 vcc, 0, v136
	v_exp_f32_e32 v138, v138
	v_pk_fma_f32 v[126:127], v[124:125], s[12:13], v[120:121] op_sel_hi:[1,0,0]
	v_exp_f32_e32 v139, v139
	v_pk_fma_f32 v[126:127], v[124:125], v[126:127], s[8:9] op_sel_hi:[1,1,0]
	s_nop 0
	v_pk_fma_f32 v[126:127], v[124:125], v[126:127], s[24:25] op_sel_hi:[1,1,0]
	s_nop 0
	v_pk_fma_f32 v[126:127], v[124:125], v[126:127], s[56:57] op_sel_hi:[1,1,0]
	s_nop 0
	v_pk_mul_f32 v[124:125], v[124:125], v[126:127]
	v_pk_mul_f32 v[126:127], v[122:123], v[122:123]
	v_pk_mul_f32 v[124:125], v[138:139], v[124:125]
	v_pk_mul_f32 v[126:127], v[126:127], s[58:59] op_sel_hi:[1,0]
	v_pk_mul_f32 v[138:139], v[136:137], v[124:125]
	v_pk_fma_f32 v[124:125], v[136:137], v[124:125], v[136:137] neg_lo:[1,0,0] neg_hi:[1,0,0]
	v_exp_f32_e32 v126, v126
	v_cndmask_b32_e32 v138, v124, v138, vcc
	v_cmp_gt_f32_e32 vcc, 0, v137
	v_and_b32_e32 v124, 0x7fffffff, v122
	v_exp_f32_e32 v127, v127
	v_cndmask_b32_e32 v139, v125, v139, vcc
	v_and_b32_e32 v125, 0x7fffffff, v123
	v_pk_fma_f32 v[124:125], v[124:125], s[36:37], 1.0 op_sel_hi:[1,0,0]
	v_cmp_gt_f32_e32 vcc, 0, v122
	v_rcp_f32_e32 v124, v124
	v_rcp_f32_e32 v125, v125
	s_nop 0
	v_pk_fma_f32 v[136:137], v[124:125], s[12:13], v[120:121] op_sel_hi:[1,0,0]
	s_nop 0
	v_pk_fma_f32 v[136:137], v[124:125], v[136:137], s[8:9] op_sel_hi:[1,1,0]
	s_nop 0
	v_pk_fma_f32 v[136:137], v[124:125], v[136:137], s[24:25] op_sel_hi:[1,1,0]
	s_nop 0
	v_pk_fma_f32 v[136:137], v[124:125], v[136:137], s[56:57] op_sel_hi:[1,1,0]
	s_nop 0
	v_pk_mul_f32 v[124:125], v[124:125], v[136:137]
	s_nop 0
; __device__ __forceinline__ unsigned pkbf(float lo, float hi) { unsigned r; asm("v_cvt_pk_bf16_f32 %0, %1, %2" : "=v"(r) : "v"(lo), "v"(hi)); return r; }
; __device__ __forceinline__ f32x2 gelu_pk(f32x2 v) {
;     const f32x2 av = __builtin_elementwise_abs(v), d = av * 0.2316418882f + 1.0f;
;     f32x2 t; t.x = __builtin_amdgcn_rcpf(d.x); t.y = __builtin_amdgcn_rcpf(d.y);
;     f32x2 q = t * 0.5307027145f + (-0.7265760135f); q = q * t + 0.7107068705f; q = q * t + (-0.142248368f); q = q * t + 0.127414796f; q = q * t;
;     const f32x2 s = (v * v) * (-0.72134752044f);
;     f32x2 e; e.x = __builtin_amdgcn_exp2f(s.x); e.y = __builtin_amdgcn_exp2f(s.y);
;     const f32x2 m = v * (q * e), r = v - m;
;     f32x2 o; o.x = v.x < 0.f ? m.x : r.x; o.y = v.y < 0.f ? m.y : r.y; return o;
; }
;     __device__ __forceinline__ void operator()(const f32x4 (&acc)[2][2][4][2], const Unit& u, int wr, int wc, int fr, int fq) const {
;     ...
;                 for (int m = 0; m < 4; ++m) { const int row = row0 + ai * HALF + m * 16; const float rs = rinv[row]; bf16_t* rowp = base + (size_t)row * 512;
; #pragma unroll
;                     for (int bj = 0; bj < 2; ++bj) { f32x4 v0 = acc[ai][bj][m][0] * rs, v1 = acc[ai][bj][m][1] * rs;
;                         f32x2 a = gelu_pk((f32x2){v0[0], v0[1]}), b = gelu_pk((f32x2){v0[2], v0[3]}), c = gelu_pk((f32x2){v1[0], v1[1]}), d = gelu_pk((f32x2){v1[2], v1[3]});
;                         u32x4 w; w.x = pkbf(a.x, a.y); w.y = pkbf(b.x, b.y); w.z = pkbf(c.x, c.y); w.w = pkbf(d.x, d.y);
;                         *(u32x4*)(rowp + bj * HALF) = w; } }
	v_pk_mul_f32 v[124:125], v[126:127], v[124:125]
	s_nop 0
	v_pk_mul_f32 v[126:127], v[122:123], v[124:125]
	v_pk_fma_f32 v[124:125], v[122:123], v[124:125], v[122:123] neg_lo:[1,0,0] neg_hi:[1,0,0]
	v_cvt_pk_bf16_f32 v122, v135, v142
	s_nop 0
	v_cndmask_b32_e32 v126, v124, v126, vcc
	v_cmp_gt_f32_e32 vcc, 0, v123
	v_cvt_pk_bf16_f32 v123, v140, v141
	v_cvt_pk_bf16_f32 v124, v138, v139
	s_nop 1
	v_cndmask_b32_e32 v125, v125, v127, vcc
	v_cvt_pk_bf16_f32 v125, v126, v125
	flat_store_dwordx4 v[128:129], v[122:125]
	v_pk_mul_f32 v[126:127], v[116:117], v[116:117]
	v_cmp_gt_f32_e32 vcc, 0, v116
	v_and_b32_e32 v123, 0x7fffffff, v117
	v_and_b32_e32 v122, 0x7fffffff, v116
	v_pk_fma_f32 v[122:123], v[122:123], s[36:37], 1.0 op_sel_hi:[1,0,0]
	v_pk_mul_f32 v[126:127], v[126:127], s[58:59] op_sel_hi:[1,0]
	v_rcp_f32_e32 v122, v122
	v_rcp_f32_e32 v123, v123
	v_exp_f32_e32 v126, v126
	v_exp_f32_e32 v127, v127
	v_pk_fma_f32 v[124:125], v[122:123], s[12:13], v[120:121] op_sel_hi:[1,0,0]
	s_nop 0
	v_pk_fma_f32 v[124:125], v[122:123], v[124:125], s[8:9] op_sel_hi:[1,1,0]
	s_nop 0
	v_pk_fma_f32 v[124:125], v[122:123], v[124:125], s[24:25] op_sel_hi:[1,1,0]
	s_nop 0
	v_pk_fma_f32 v[124:125], v[122:123], v[124:125], s[56:57] op_sel_hi:[1,1,0]
	s_nop 0
	v_pk_mul_f32 v[122:123], v[122:123], v[124:125]
	v_pk_mul_f32 v[124:125], v[118:119], v[118:119]
	v_pk_mul_f32 v[122:123], v[126:127], v[122:123]
	s_nop 0
	v_pk_mul_f32 v[126:127], v[116:117], v[122:123]
	v_pk_fma_f32 v[122:123], v[116:117], v[122:123], v[116:117] neg_lo:[1,0,0] neg_hi:[1,0,0]
	v_and_b32_e32 v116, 0x7fffffff, v118
	v_cndmask_b32_e32 v126, v122, v126, vcc
	v_cmp_gt_f32_e32 vcc, 0, v117
	v_and_b32_e32 v117, 0x7fffffff, v119
	v_pk_fma_f32 v[116:117], v[116:117], s[36:37], 1.0 op_sel_hi:[1,0,0]
	v_cndmask_b32_e32 v127, v123, v127, vcc
	v_rcp_f32_e32 v116, v116
	v_rcp_f32_e32 v117, v117
	v_cmp_gt_f32_e32 vcc, 0, v118
	v_pk_fma_f32 v[122:123], v[116:117], s[12:13], v[120:121] op_sel_hi:[1,0,0]
	s_nop 0
	v_pk_fma_f32 v[122:123], v[116:117], v[122:123], s[8:9] op_sel_hi:[1,1,0]
	s_nop 0
	v_pk_fma_f32 v[122:123], v[116:117], v[122:123], s[24:25] op_sel_hi:[1,1,0]
	s_nop 0
	v_pk_fma_f32 v[122:123], v[116:117], v[122:123], s[56:57] op_sel_hi:[1,1,0]
	s_nop 0
	v_pk_mul_f32 v[116:117], v[116:117], v[122:123]
	v_pk_mul_f32 v[122:123], v[124:125], s[58:59] op_sel_hi:[1,0]
	s_nop 0
	v_exp_f32_e32 v122, v122
	v_exp_f32_e32 v123, v123
	s_nop 0
	v_pk_mul_f32 v[116:117], v[122:123], v[116:117]
	s_nop 0
	v_pk_mul_f32 v[122:123], v[118:119], v[116:117]
	v_pk_fma_f32 v[116:117], v[118:119], v[116:117], v[118:119] neg_lo:[1,0,0] neg_hi:[1,0,0]
	s_nop 0
	v_cndmask_b32_e32 v124, v116, v122, vcc
	v_cmp_gt_f32_e32 vcc, 0, v119
	v_and_b32_e32 v116, 0x7fffffff, v112
	s_nop 0
	v_cndmask_b32_e32 v125, v117, v123, vcc
	v_and_b32_e32 v117, 0x7fffffff, v113
	v_pk_fma_f32 v[116:117], v[116:117], s[36:37], 1.0 op_sel_hi:[1,0,0]
	v_pk_mul_f32 v[122:123], v[112:113], v[112:113]
	v_rcp_f32_e32 v116, v116
	v_rcp_f32_e32 v117, v117
	v_pk_mul_f32 v[122:123], v[122:123], s[58:59] op_sel_hi:[1,0]
	v_cmp_gt_f32_e32 vcc, 0, v112
	v_exp_f32_e32 v122, v122
	v_pk_fma_f32 v[118:119], v[116:117], s[12:13], v[120:121] op_sel_hi:[1,0,0]
	v_exp_f32_e32 v123, v123
	v_pk_fma_f32 v[118:119], v[116:117], v[118:119], s[8:9] op_sel_hi:[1,1,0]
	s_nop 0
	v_pk_fma_f32 v[118:119], v[116:117], v[118:119], s[24:25] op_sel_hi:[1,1,0]
	s_nop 0
	v_pk_fma_f32 v[118:119], v[116:117], v[118:119], s[56:57] op_sel_hi:[1,1,0]
	s_nop 0
	v_pk_mul_f32 v[116:117], v[116:117], v[118:119]
	v_pk_mul_f32 v[118:119], v[114:115], v[114:115]
	v_pk_mul_f32 v[116:117], v[122:123], v[116:117]
	s_nop 0
	v_pk_mul_f32 v[122:123], v[112:113], v[116:117]
	v_pk_fma_f32 v[116:117], v[112:113], v[116:117], v[112:113] neg_lo:[1,0,0] neg_hi:[1,0,0]
	v_and_b32_e32 v112, 0x7fffffff, v114
	v_cndmask_b32_e32 v122, v116, v122, vcc
	v_cmp_gt_f32_e32 vcc, 0, v113
	v_and_b32_e32 v113, 0x7fffffff, v115
	v_pk_fma_f32 v[112:113], v[112:113], s[36:37], 1.0 op_sel_hi:[1,0,0]
	v_cndmask_b32_e32 v123, v117, v123, vcc
	v_rcp_f32_e32 v112, v112
	v_rcp_f32_e32 v113, v113
	v_cmp_gt_f32_e32 vcc, 0, v114
	v_pk_fma_f32 v[116:117], v[112:113], s[12:13], v[120:121] op_sel_hi:[1,0,0]
	s_nop 0
	v_pk_fma_f32 v[116:117], v[112:113], v[116:117], s[8:9] op_sel_hi:[1,1,0]
	s_nop 0
	v_pk_fma_f32 v[116:117], v[112:113], v[116:117], s[24:25] op_sel_hi:[1,1,0]
	s_nop 0
	v_pk_fma_f32 v[116:117], v[112:113], v[116:117], s[56:57] op_sel_hi:[1,1,0]
	s_nop 0
	v_pk_mul_f32 v[112:113], v[112:113], v[116:117]
	v_pk_mul_f32 v[116:117], v[118:119], s[58:59] op_sel_hi:[1,0]
	s_nop 0
	v_exp_f32_e32 v116, v116
	v_exp_f32_e32 v117, v117
	s_nop 0
	v_pk_mul_f32 v[112:113], v[116:117], v[112:113]
	s_nop 0
	v_pk_mul_f32 v[116:117], v[114:115], v[112:113]
	v_pk_fma_f32 v[112:113], v[114:115], v[112:113], v[114:115] neg_lo:[1,0,0] neg_hi:[1,0,0]
	v_cvt_pk_bf16_f32 v114, v122, v123
	s_nop 0
	v_cndmask_b32_e32 v116, v112, v116, vcc
	v_cmp_gt_f32_e32 vcc, 0, v115
	v_cvt_pk_bf16_f32 v112, v126, v127
	s_nop 1
	v_cndmask_b32_e32 v115, v113, v117, vcc
	v_cvt_pk_bf16_f32 v113, v124, v125
	v_cvt_pk_bf16_f32 v115, v116, v115
	flat_store_dwordx4 v[128:129], v[112:115] offset:256
	s_nop 1
	v_or_b32_e32 v112, 16, v158
	v_ashrrev_i32_e32 v113, 31, v112
	v_lshl_add_u64 v[114:115], v[112:113], 2, s[40:41]
	s_nop 0
	v_lshlrev_b64 v[112:113], 10, v[112:113]
	v_lshl_add_u64 v[112:113], v[132:133], 0, v[112:113]
	s_nop 0
	v_pk_mul_f32 v[108:109], v[108:109], v[168:169] op_sel_hi:[1,0]
	v_pk_mul_f32 v[116:117], v[104:105], v[168:169] op_sel_hi:[1,0]
	v_and_b32_e32 v105, 0x7fffffff, v109
	v_and_b32_e32 v104, 0x7fffffff, v108
	v_pk_fma_f32 v[104:105], v[104:105], s[36:37], 1.0 op_sel_hi:[1,0,0]
; __device__ __forceinline__ unsigned pkbf(float lo, float hi) { unsigned r; asm("v_cvt_pk_bf16_f32 %0, %1, %2" : "=v"(r) : "v"(lo), "v"(hi)); return r; }
; __device__ __forceinline__ f32x2 gelu_pk(f32x2 v) {
;     const f32x2 av = __builtin_elementwise_abs(v), d = av * 0.2316418882f + 1.0f;
;     f32x2 t; t.x = __builtin_amdgcn_rcpf(d.x); t.y = __builtin_amdgcn_rcpf(d.y);
;     f32x2 q = t * 0.5307027145f + (-0.7265760135f); q = q * t + 0.7107068705f; q = q * t + (-0.142248368f); q = q * t + 0.127414796f; q = q * t;
;     const f32x2 s = (v * v) * (-0.72134752044f);
;     f32x2 e; e.x = __builtin_amdgcn_exp2f(s.x); e.y = __builtin_amdgcn_exp2f(s.y);
;     const f32x2 m = v * (q * e), r = v - m;
;     f32x2 o; o.x = v.x < 0.f ? m.x : r.x; o.y = v.y < 0.f ? m.y : r.y; return o;
; }
;     __device__ __forceinline__ void operator()(const f32x4 (&acc)[2][2][4][2], const Unit& u, int wr, int wc, int fr, int fq) const {
;     ...
;                 for (int m = 0; m < 4; ++m) { const int row = row0 + ai * HALF + m * 16; const float rs = rinv[row]; bf16_t* rowp = base + (size_t)row * 512;
; #pragma unroll
;                     for (int bj = 0; bj < 2; ++bj) { f32x4 v0 = acc[ai][bj][m][0] * rs, v1 = acc[ai][bj][m][1] * rs;
;                         f32x2 a = gelu_pk((f32x2){v0[0], v0[1]}), b = gelu_pk((f32x2){v0[2], v0[3]}), c = gelu_pk((f32x2){v1[0], v1[1]}), d = gelu_pk((f32x2){v1[2], v1[3]});
;                         u32x4 w; w.x = pkbf(a.x, a.y); w.y = pkbf(b.x, b.y); w.z = pkbf(c.x, c.y); w.w = pkbf(d.x, d.y);
;                         *(u32x4*)(rowp + bj * HALF) = w; } }
	v_pk_mul_f32 v[122:123], v[108:109], v[108:109]
	v_rcp_f32_e32 v104, v104
	v_rcp_f32_e32 v105, v105
	v_pk_mul_f32 v[122:123], v[122:123], s[58:59] op_sel_hi:[1,0]
	v_pk_mul_f32 v[110:111], v[110:111], v[168:169] op_sel_hi:[1,0]
	v_exp_f32_e32 v122, v122
	v_pk_fma_f32 v[118:119], v[104:105], s[12:13], v[120:121] op_sel_hi:[1,0,0]
	v_exp_f32_e32 v123, v123
	v_pk_fma_f32 v[118:119], v[104:105], v[118:119], s[8:9] op_sel_hi:[1,1,0]
	v_cmp_gt_f32_e32 vcc, 0, v108
	v_pk_fma_f32 v[118:119], v[104:105], v[118:119], s[24:25] op_sel_hi:[1,1,0]
	v_pk_mul_f32 v[106:107], v[106:107], v[168:169] op_sel_hi:[1,0]
	v_pk_fma_f32 v[118:119], v[104:105], v[118:119], s[56:57] op_sel_hi:[1,1,0]
	s_nop 0
	v_pk_mul_f32 v[104:105], v[104:105], v[118:119]
	v_pk_mul_f32 v[118:119], v[110:111], v[110:111]
	v_pk_mul_f32 v[104:105], v[122:123], v[104:105]
	v_pk_mul_f32 v[118:119], v[118:119], s[58:59] op_sel_hi:[1,0]
	v_pk_mul_f32 v[122:123], v[108:109], v[104:105]
	v_pk_fma_f32 v[104:105], v[108:109], v[104:105], v[108:109] neg_lo:[1,0,0] neg_hi:[1,0,0]
	v_and_b32_e32 v108, 0x7fffffff, v110
	v_cndmask_b32_e32 v104, v104, v122, vcc
	v_cmp_gt_f32_e32 vcc, 0, v109
	v_and_b32_e32 v109, 0x7fffffff, v111
	v_pk_fma_f32 v[108:109], v[108:109], s[36:37], 1.0 op_sel_hi:[1,0,0]
	v_cndmask_b32_e32 v105, v105, v123, vcc
	v_rcp_f32_e32 v108, v108
	v_rcp_f32_e32 v109, v109
	v_exp_f32_e32 v118, v118
	v_exp_f32_e32 v119, v119
	v_cmp_gt_f32_e32 vcc, 0, v110
	v_pk_fma_f32 v[122:123], v[108:109], s[12:13], v[120:121] op_sel_hi:[1,0,0]
	v_cvt_pk_bf16_f32 v104, v104, v105
	s_nop 0
	v_pk_fma_f32 v[122:123], v[108:109], v[122:123], s[8:9] op_sel_hi:[1,1,0]
	s_nop 0
	v_pk_fma_f32 v[122:123], v[108:109], v[122:123], s[24:25] op_sel_hi:[1,1,0]
	s_nop 0
	v_pk_fma_f32 v[122:123], v[108:109], v[122:123], s[56:57] op_sel_hi:[1,1,0]
	s_nop 0
	v_pk_mul_f32 v[108:109], v[108:109], v[122:123]
	s_nop 0
	v_pk_mul_f32 v[108:109], v[118:119], v[108:109]
	s_nop 0
	v_pk_mul_f32 v[118:119], v[110:111], v[108:109]
	v_pk_fma_f32 v[108:109], v[110:111], v[108:109], v[110:111] neg_lo:[1,0,0] neg_hi:[1,0,0]
	s_nop 0
	v_cndmask_b32_e32 v115, v108, v118, vcc
	v_cmp_gt_f32_e32 vcc, 0, v111
	v_and_b32_e32 v108, 0x7fffffff, v116
	v_pk_mul_f32 v[100:101], v[100:101], v[168:169] op_sel_hi:[1,0]
	v_cndmask_b32_e32 v122, v109, v119, vcc
	v_and_b32_e32 v109, 0x7fffffff, v117
	v_pk_fma_f32 v[108:109], v[108:109], s[36:37], 1.0 op_sel_hi:[1,0,0]
	v_pk_mul_f32 v[118:119], v[116:117], v[116:117]
	v_rcp_f32_e32 v108, v108
	v_rcp_f32_e32 v109, v109
	v_pk_mul_f32 v[118:119], v[118:119], s[58:59] op_sel_hi:[1,0]
	v_cmp_gt_f32_e32 vcc, 0, v116
	v_exp_f32_e32 v118, v118
	v_pk_fma_f32 v[110:111], v[108:109], s[12:13], v[120:121] op_sel_hi:[1,0,0]
	v_exp_f32_e32 v119, v119
	v_pk_fma_f32 v[110:111], v[108:109], v[110:111], s[8:9] op_sel_hi:[1,1,0]
	v_cvt_pk_bf16_f32 v105, v115, v122
	v_pk_mul_f32 v[102:103], v[102:103], v[168:169] op_sel_hi:[1,0]
	v_pk_fma_f32 v[110:111], v[108:109], v[110:111], s[24:25] op_sel_hi:[1,1,0]
	v_pk_mul_f32 v[96:97], v[96:97], v[168:169] op_sel_hi:[1,0]
	v_pk_fma_f32 v[110:111], v[108:109], v[110:111], s[56:57] op_sel_hi:[1,1,0]
	v_pk_mul_f32 v[98:99], v[98:99], v[168:169] op_sel_hi:[1,0]
	v_pk_mul_f32 v[108:109], v[108:109], v[110:111]
	v_pk_mul_f32 v[110:111], v[106:107], v[106:107]
	v_pk_mul_f32 v[108:109], v[118:119], v[108:109]
	v_pk_mul_f32 v[110:111], v[110:111], s[58:59] op_sel_hi:[1,0]
	v_pk_mul_f32 v[118:119], v[116:117], v[108:109]
	v_pk_fma_f32 v[108:109], v[116:117], v[108:109], v[116:117] neg_lo:[1,0,0] neg_hi:[1,0,0]
	v_exp_f32_e32 v110, v110
	v_cndmask_b32_e32 v118, v108, v118, vcc
	v_cmp_gt_f32_e32 vcc, 0, v117
	v_and_b32_e32 v108, 0x7fffffff, v106
	v_exp_f32_e32 v111, v111
	v_cndmask_b32_e32 v119, v109, v119, vcc
	v_and_b32_e32 v109, 0x7fffffff, v107
	v_pk_fma_f32 v[108:109], v[108:109], s[36:37], 1.0 op_sel_hi:[1,0,0]
	v_cmp_gt_f32_e32 vcc, 0, v106
	v_rcp_f32_e32 v108, v108
	v_rcp_f32_e32 v109, v109
	s_nop 0
	v_pk_fma_f32 v[116:117], v[108:109], s[12:13], v[120:121] op_sel_hi:[1,0,0]
	s_nop 0
	v_pk_fma_f32 v[116:117], v[108:109], v[116:117], s[8:9] op_sel_hi:[1,1,0]
	s_nop 0
	v_pk_fma_f32 v[116:117], v[108:109], v[116:117], s[24:25] op_sel_hi:[1,1,0]
	s_nop 0
	v_pk_fma_f32 v[116:117], v[108:109], v[116:117], s[56:57] op_sel_hi:[1,1,0]
	s_nop 0
	v_pk_mul_f32 v[108:109], v[108:109], v[116:117]
	s_nop 0
	v_pk_mul_f32 v[108:109], v[110:111], v[108:109]
	s_nop 0
	v_pk_mul_f32 v[110:111], v[106:107], v[108:109]
	v_pk_fma_f32 v[108:109], v[106:107], v[108:109], v[106:107] neg_lo:[1,0,0] neg_hi:[1,0,0]
	v_cvt_pk_bf16_f32 v106, v118, v119
	s_nop 0
	v_cndmask_b32_e32 v108, v108, v110, vcc
	v_cmp_gt_f32_e32 vcc, 0, v107
	s_nop 1
	v_cndmask_b32_e32 v107, v109, v111, vcc
	v_cvt_pk_bf16_f32 v107, v108, v107
	flat_store_dwordx4 v[112:113], v[104:107]
	v_pk_mul_f32 v[108:109], v[100:101], v[100:101]
	v_cmp_gt_f32_e32 vcc, 0, v100
	v_and_b32_e32 v105, 0x7fffffff, v101
	v_and_b32_e32 v104, 0x7fffffff, v100
	v_pk_fma_f32 v[104:105], v[104:105], s[36:37], 1.0 op_sel_hi:[1,0,0]
	v_pk_mul_f32 v[108:109], v[108:109], s[58:59] op_sel_hi:[1,0]
	v_rcp_f32_e32 v104, v104
	v_rcp_f32_e32 v105, v105
	v_exp_f32_e32 v108, v108
	v_exp_f32_e32 v109, v109
	v_pk_fma_f32 v[106:107], v[104:105], s[12:13], v[120:121] op_sel_hi:[1,0,0]
	s_nop 0
	v_pk_fma_f32 v[106:107], v[104:105], v[106:107], s[8:9] op_sel_hi:[1,1,0]
	s_nop 0
	v_pk_fma_f32 v[106:107], v[104:105], v[106:107], s[24:25] op_sel_hi:[1,1,0]
	s_nop 0
	v_pk_fma_f32 v[106:107], v[104:105], v[106:107], s[56:57] op_sel_hi:[1,1,0]
	s_nop 0
	v_pk_mul_f32 v[104:105], v[104:105], v[106:107]
	v_pk_mul_f32 v[106:107], v[102:103], v[102:103]
	v_pk_mul_f32 v[104:105], v[108:109], v[104:105]
; __device__ __forceinline__ unsigned pkbf(float lo, float hi) { unsigned r; asm("v_cvt_pk_bf16_f32 %0, %1, %2" : "=v"(r) : "v"(lo), "v"(hi)); return r; }
; __device__ __forceinline__ f32x2 gelu_pk(f32x2 v) {
;     const f32x2 av = __builtin_elementwise_abs(v), d = av * 0.2316418882f + 1.0f;
;     f32x2 t; t.x = __builtin_amdgcn_rcpf(d.x); t.y = __builtin_amdgcn_rcpf(d.y);
;     f32x2 q = t * 0.5307027145f + (-0.7265760135f); q = q * t + 0.7107068705f; q = q * t + (-0.142248368f); q = q * t + 0.127414796f; q = q * t;
;     const f32x2 s = (v * v) * (-0.72134752044f);
;     f32x2 e; e.x = __builtin_amdgcn_exp2f(s.x); e.y = __builtin_amdgcn_exp2f(s.y);
;     const f32x2 m = v * (q * e), r = v - m;
;     f32x2 o; o.x = v.x < 0.f ? m.x : r.x; o.y = v.y < 0.f ? m.y : r.y; return o;
; }
;     __device__ __forceinline__ void operator()(const f32x4 (&acc)[2][2][4][2], const Unit& u, int wr, int wc, int fr, int fq) const {
;     ...
;                 for (int m = 0; m < 4; ++m) { const int row = row0 + ai * HALF + m * 16; const float rs = rinv[row]; bf16_t* rowp = base + (size_t)row * 512;
; #pragma unroll
;                     for (int bj = 0; bj < 2; ++bj) { f32x4 v0 = acc[ai][bj][m][0] * rs, v1 = acc[ai][bj][m][1] * rs;
;                         f32x2 a = gelu_pk((f32x2){v0[0], v0[1]}), b = gelu_pk((f32x2){v0[2], v0[3]}), c = gelu_pk((f32x2){v1[0], v1[1]}), d = gelu_pk((f32x2){v1[2], v1[3]});
;                         u32x4 w; w.x = pkbf(a.x, a.y); w.y = pkbf(b.x, b.y); w.z = pkbf(c.x, c.y); w.w = pkbf(d.x, d.y);
;                         *(u32x4*)(rowp + bj * HALF) = w; } }
	s_nop 0
	v_pk_mul_f32 v[108:109], v[100:101], v[104:105]
	v_pk_fma_f32 v[104:105], v[100:101], v[104:105], v[100:101] neg_lo:[1,0,0] neg_hi:[1,0,0]
	v_and_b32_e32 v100, 0x7fffffff, v102
	v_cndmask_b32_e32 v108, v104, v108, vcc
	v_cmp_gt_f32_e32 vcc, 0, v101
	v_and_b32_e32 v101, 0x7fffffff, v103
	v_pk_fma_f32 v[100:101], v[100:101], s[36:37], 1.0 op_sel_hi:[1,0,0]
	v_cndmask_b32_e32 v109, v105, v109, vcc
	v_rcp_f32_e32 v100, v100
	v_rcp_f32_e32 v101, v101
	v_cmp_gt_f32_e32 vcc, 0, v102
	v_pk_fma_f32 v[104:105], v[100:101], s[12:13], v[120:121] op_sel_hi:[1,0,0]
	s_nop 0
	v_pk_fma_f32 v[104:105], v[100:101], v[104:105], s[8:9] op_sel_hi:[1,1,0]
	s_nop 0
	v_pk_fma_f32 v[104:105], v[100:101], v[104:105], s[24:25] op_sel_hi:[1,1,0]
	s_nop 0
	v_pk_fma_f32 v[104:105], v[100:101], v[104:105], s[56:57] op_sel_hi:[1,1,0]
	s_nop 0
	v_pk_mul_f32 v[100:101], v[100:101], v[104:105]
	v_pk_mul_f32 v[104:105], v[106:107], s[58:59] op_sel_hi:[1,0]
	s_nop 0
	v_exp_f32_e32 v104, v104
	v_exp_f32_e32 v105, v105
	s_nop 0
	v_pk_mul_f32 v[100:101], v[104:105], v[100:101]
	s_nop 0
	v_pk_mul_f32 v[104:105], v[102:103], v[100:101]
	v_pk_fma_f32 v[100:101], v[102:103], v[100:101], v[102:103] neg_lo:[1,0,0] neg_hi:[1,0,0]
	s_nop 0
	v_cndmask_b32_e32 v106, v100, v104, vcc
	v_cmp_gt_f32_e32 vcc, 0, v103
	v_and_b32_e32 v100, 0x7fffffff, v96
	s_nop 0
	v_cndmask_b32_e32 v107, v101, v105, vcc
	v_and_b32_e32 v101, 0x7fffffff, v97
	v_pk_fma_f32 v[100:101], v[100:101], s[36:37], 1.0 op_sel_hi:[1,0,0]
	v_pk_mul_f32 v[104:105], v[96:97], v[96:97]
	v_rcp_f32_e32 v100, v100
	v_rcp_f32_e32 v101, v101
	v_pk_mul_f32 v[104:105], v[104:105], s[58:59] op_sel_hi:[1,0]
	v_cmp_gt_f32_e32 vcc, 0, v96
	v_exp_f32_e32 v104, v104
	v_pk_fma_f32 v[102:103], v[100:101], s[12:13], v[120:121] op_sel_hi:[1,0,0]
	v_exp_f32_e32 v105, v105
	v_pk_fma_f32 v[102:103], v[100:101], v[102:103], s[8:9] op_sel_hi:[1,1,0]
	s_nop 0
	v_pk_fma_f32 v[102:103], v[100:101], v[102:103], s[24:25] op_sel_hi:[1,1,0]
	s_nop 0
	v_pk_fma_f32 v[102:103], v[100:101], v[102:103], s[56:57] op_sel_hi:[1,1,0]
	s_nop 0
	v_pk_mul_f32 v[100:101], v[100:101], v[102:103]
	v_pk_mul_f32 v[102:103], v[98:99], v[98:99]
	v_pk_mul_f32 v[100:101], v[104:105], v[100:101]
	s_nop 0
	v_pk_mul_f32 v[104:105], v[96:97], v[100:101]
	v_pk_fma_f32 v[100:101], v[96:97], v[100:101], v[96:97] neg_lo:[1,0,0] neg_hi:[1,0,0]
	v_and_b32_e32 v96, 0x7fffffff, v98
	v_cndmask_b32_e32 v104, v100, v104, vcc
	v_cmp_gt_f32_e32 vcc, 0, v97
	v_and_b32_e32 v97, 0x7fffffff, v99
	v_pk_fma_f32 v[96:97], v[96:97], s[36:37], 1.0 op_sel_hi:[1,0,0]
	v_cndmask_b32_e32 v105, v101, v105, vcc
	v_rcp_f32_e32 v96, v96
	v_rcp_f32_e32 v97, v97
	v_cmp_gt_f32_e32 vcc, 0, v98
	v_pk_fma_f32 v[100:101], v[96:97], s[12:13], v[120:121] op_sel_hi:[1,0,0]
	s_nop 0
	v_pk_fma_f32 v[100:101], v[96:97], v[100:101], s[8:9] op_sel_hi:[1,1,0]
	s_nop 0
	v_pk_fma_f32 v[100:101], v[96:97], v[100:101], s[24:25] op_sel_hi:[1,1,0]
	s_nop 0
	v_pk_fma_f32 v[100:101], v[96:97], v[100:101], s[56:57] op_sel_hi:[1,1,0]
	s_nop 0
	v_pk_mul_f32 v[96:97], v[96:97], v[100:101]
	v_pk_mul_f32 v[100:101], v[102:103], s[58:59] op_sel_hi:[1,0]
	s_nop 0
	v_exp_f32_e32 v100, v100
	v_exp_f32_e32 v101, v101
	s_nop 0
	v_pk_mul_f32 v[96:97], v[100:101], v[96:97]
	s_nop 0
	v_pk_mul_f32 v[100:101], v[98:99], v[96:97]
	v_pk_fma_f32 v[96:97], v[98:99], v[96:97], v[98:99] neg_lo:[1,0,0] neg_hi:[1,0,0]
	v_cvt_pk_bf16_f32 v98, v104, v105
	s_nop 0
	v_cndmask_b32_e32 v100, v96, v100, vcc
	v_cmp_gt_f32_e32 vcc, 0, v99
	v_cvt_pk_bf16_f32 v96, v108, v109
	s_nop 1
	v_cndmask_b32_e32 v99, v97, v101, vcc
	v_cvt_pk_bf16_f32 v97, v106, v107
	v_cvt_pk_bf16_f32 v99, v100, v99
	flat_store_dwordx4 v[112:113], v[96:99] offset:256
	s_nop 1
	v_or_b32_e32 v96, 32, v158
	v_ashrrev_i32_e32 v97, 31, v96
	v_lshl_add_u64 v[98:99], v[96:97], 2, s[40:41]
	s_nop 0
	v_lshlrev_b64 v[96:97], 10, v[96:97]
	v_lshl_add_u64 v[96:97], v[132:133], 0, v[96:97]
	s_nop 0
	v_pk_mul_f32 v[92:93], v[92:93], v[170:171] op_sel_hi:[1,0]
	s_nop 0
	v_and_b32_e32 v101, 0x7fffffff, v93
	v_and_b32_e32 v100, 0x7fffffff, v92
	v_pk_fma_f32 v[100:101], v[100:101], s[36:37], 1.0 op_sel_hi:[1,0,0]
	v_pk_mul_f32 v[104:105], v[92:93], v[92:93]
	v_rcp_f32_e32 v100, v100
	v_rcp_f32_e32 v101, v101
	v_pk_mul_f32 v[104:105], v[104:105], s[58:59] op_sel_hi:[1,0]
	v_pk_mul_f32 v[94:95], v[94:95], v[170:171] op_sel_hi:[1,0]
	v_exp_f32_e32 v104, v104
	v_pk_fma_f32 v[102:103], v[100:101], s[12:13], v[120:121] op_sel_hi:[1,0,0]
	v_exp_f32_e32 v105, v105
	v_pk_fma_f32 v[102:103], v[100:101], v[102:103], s[8:9] op_sel_hi:[1,1,0]
	v_cmp_gt_f32_e32 vcc, 0, v92
	v_pk_fma_f32 v[102:103], v[100:101], v[102:103], s[24:25] op_sel_hi:[1,1,0]
	v_pk_mul_f32 v[90:91], v[90:91], v[170:171] op_sel_hi:[1,0]
	v_pk_fma_f32 v[102:103], v[100:101], v[102:103], s[56:57] op_sel_hi:[1,1,0]
	v_pk_mul_f32 v[88:89], v[88:89], v[170:171] op_sel_hi:[1,0]
	v_pk_mul_f32 v[100:101], v[100:101], v[102:103]
	v_pk_mul_f32 v[102:103], v[94:95], v[94:95]
	v_pk_mul_f32 v[100:101], v[104:105], v[100:101]
	s_nop 0
	v_pk_mul_f32 v[104:105], v[92:93], v[100:101]
	v_pk_fma_f32 v[100:101], v[92:93], v[100:101], v[92:93] neg_lo:[1,0,0] neg_hi:[1,0,0]
	v_and_b32_e32 v92, 0x7fffffff, v94
	v_cndmask_b32_e32 v99, v100, v104, vcc
	v_cmp_gt_f32_e32 vcc, 0, v93
	v_and_b32_e32 v93, 0x7fffffff, v95
	v_pk_fma_f32 v[92:93], v[92:93], s[36:37], 1.0 op_sel_hi:[1,0,0]
	v_cndmask_b32_e32 v104, v101, v105, vcc
	v_rcp_f32_e32 v92, v92
	v_rcp_f32_e32 v93, v93
	v_cmp_gt_f32_e32 vcc, 0, v94
	v_pk_mul_f32 v[84:85], v[84:85], v[170:171] op_sel_hi:[1,0]
	v_pk_mul_f32 v[86:87], v[86:87], v[170:171] op_sel_hi:[1,0]
	v_pk_fma_f32 v[100:101], v[92:93], s[12:13], v[120:121] op_sel_hi:[1,0,0]
; __device__ __forceinline__ unsigned pkbf(float lo, float hi) { unsigned r; asm("v_cvt_pk_bf16_f32 %0, %1, %2" : "=v"(r) : "v"(lo), "v"(hi)); return r; }
; __device__ __forceinline__ f32x2 gelu_pk(f32x2 v) {
;     const f32x2 av = __builtin_elementwise_abs(v), d = av * 0.2316418882f + 1.0f;
;     f32x2 t; t.x = __builtin_amdgcn_rcpf(d.x); t.y = __builtin_amdgcn_rcpf(d.y);
;     f32x2 q = t * 0.5307027145f + (-0.7265760135f); q = q * t + 0.7107068705f; q = q * t + (-0.142248368f); q = q * t + 0.127414796f; q = q * t;
;     const f32x2 s = (v * v) * (-0.72134752044f);
;     f32x2 e; e.x = __builtin_amdgcn_exp2f(s.x); e.y = __builtin_amdgcn_exp2f(s.y);
;     const f32x2 m = v * (q * e), r = v - m;
;     f32x2 o; o.x = v.x < 0.f ? m.x : r.x; o.y = v.y < 0.f ? m.y : r.y; return o;
; }
;     __device__ __forceinline__ void operator()(const f32x4 (&acc)[2][2][4][2], const Unit& u, int wr, int wc, int fr, int fq) const {
;     ...
;                 for (int m = 0; m < 4; ++m) { const int row = row0 + ai * HALF + m * 16; const float rs = rinv[row]; bf16_t* rowp = base + (size_t)row * 512;
; #pragma unroll
;                     for (int bj = 0; bj < 2; ++bj) { f32x4 v0 = acc[ai][bj][m][0] * rs, v1 = acc[ai][bj][m][1] * rs;
;                         f32x2 a = gelu_pk((f32x2){v0[0], v0[1]}), b = gelu_pk((f32x2){v0[2], v0[3]}), c = gelu_pk((f32x2){v1[0], v1[1]}), d = gelu_pk((f32x2){v1[2], v1[3]});
;                         u32x4 w; w.x = pkbf(a.x, a.y); w.y = pkbf(b.x, b.y); w.z = pkbf(c.x, c.y); w.w = pkbf(d.x, d.y);
;                         *(u32x4*)(rowp + bj * HALF) = w; } }
	v_pk_mul_f32 v[80:81], v[80:81], v[170:171] op_sel_hi:[1,0]
	v_pk_fma_f32 v[100:101], v[92:93], v[100:101], s[8:9] op_sel_hi:[1,1,0]
	v_pk_mul_f32 v[82:83], v[82:83], v[170:171] op_sel_hi:[1,0]
	v_pk_fma_f32 v[100:101], v[92:93], v[100:101], s[24:25] op_sel_hi:[1,1,0]
	s_nop 0
	v_pk_fma_f32 v[100:101], v[92:93], v[100:101], s[56:57] op_sel_hi:[1,1,0]
	s_nop 0
	v_pk_mul_f32 v[92:93], v[92:93], v[100:101]
	v_pk_mul_f32 v[100:101], v[102:103], s[58:59] op_sel_hi:[1,0]
	s_nop 0
	v_exp_f32_e32 v100, v100
	v_exp_f32_e32 v101, v101
	s_nop 0
	v_pk_mul_f32 v[92:93], v[100:101], v[92:93]
	s_nop 0
	v_pk_mul_f32 v[100:101], v[94:95], v[92:93]
	v_pk_fma_f32 v[92:93], v[94:95], v[92:93], v[94:95] neg_lo:[1,0,0] neg_hi:[1,0,0]
	s_nop 0
	v_cndmask_b32_e32 v102, v92, v100, vcc
	v_cmp_gt_f32_e32 vcc, 0, v95
	v_and_b32_e32 v92, 0x7fffffff, v88
	s_nop 0
	v_cndmask_b32_e32 v103, v93, v101, vcc
	v_and_b32_e32 v93, 0x7fffffff, v89
	v_pk_fma_f32 v[92:93], v[92:93], s[36:37], 1.0 op_sel_hi:[1,0,0]
	v_pk_mul_f32 v[100:101], v[88:89], v[88:89]
	v_rcp_f32_e32 v92, v92
	v_rcp_f32_e32 v93, v93
	v_pk_mul_f32 v[100:101], v[100:101], s[58:59] op_sel_hi:[1,0]
	v_cmp_gt_f32_e32 vcc, 0, v88
	v_exp_f32_e32 v100, v100
	v_pk_fma_f32 v[94:95], v[92:93], s[12:13], v[120:121] op_sel_hi:[1,0,0]
	v_exp_f32_e32 v101, v101
	v_pk_fma_f32 v[94:95], v[92:93], v[94:95], s[8:9] op_sel_hi:[1,1,0]
	s_nop 0
	v_pk_fma_f32 v[94:95], v[92:93], v[94:95], s[24:25] op_sel_hi:[1,1,0]
	s_nop 0
	v_pk_fma_f32 v[94:95], v[92:93], v[94:95], s[56:57] op_sel_hi:[1,1,0]
	s_nop 0
	v_pk_mul_f32 v[92:93], v[92:93], v[94:95]
	v_pk_mul_f32 v[94:95], v[90:91], v[90:91]
	v_pk_mul_f32 v[92:93], v[100:101], v[92:93]
	s_nop 0
	v_pk_mul_f32 v[100:101], v[88:89], v[92:93]
	v_pk_fma_f32 v[92:93], v[88:89], v[92:93], v[88:89] neg_lo:[1,0,0] neg_hi:[1,0,0]
	v_and_b32_e32 v88, 0x7fffffff, v90
	v_cndmask_b32_e32 v100, v92, v100, vcc
	v_cmp_gt_f32_e32 vcc, 0, v89
	v_and_b32_e32 v89, 0x7fffffff, v91
	v_pk_fma_f32 v[88:89], v[88:89], s[36:37], 1.0 op_sel_hi:[1,0,0]
	v_cndmask_b32_e32 v101, v93, v101, vcc
	v_rcp_f32_e32 v88, v88
	v_rcp_f32_e32 v89, v89
	v_cmp_gt_f32_e32 vcc, 0, v90
	v_pk_fma_f32 v[92:93], v[88:89], s[12:13], v[120:121] op_sel_hi:[1,0,0]
	s_nop 0
	v_pk_fma_f32 v[92:93], v[88:89], v[92:93], s[8:9] op_sel_hi:[1,1,0]
	s_nop 0
	v_pk_fma_f32 v[92:93], v[88:89], v[92:93], s[24:25] op_sel_hi:[1,1,0]
	s_nop 0
	v_pk_fma_f32 v[92:93], v[88:89], v[92:93], s[56:57] op_sel_hi:[1,1,0]
	s_nop 0
	v_pk_mul_f32 v[88:89], v[88:89], v[92:93]
	v_pk_mul_f32 v[92:93], v[94:95], s[58:59] op_sel_hi:[1,0]
	s_nop 0
	v_exp_f32_e32 v92, v92
	v_exp_f32_e32 v93, v93
	s_nop 0
	v_pk_mul_f32 v[88:89], v[92:93], v[88:89]
	s_nop 0
	v_pk_mul_f32 v[92:93], v[90:91], v[88:89]
	v_pk_fma_f32 v[88:89], v[90:91], v[88:89], v[90:91] neg_lo:[1,0,0] neg_hi:[1,0,0]
	v_cvt_pk_bf16_f32 v90, v100, v101
	s_nop 0
	v_cndmask_b32_e32 v92, v88, v92, vcc
	v_cmp_gt_f32_e32 vcc, 0, v91
	v_cvt_pk_bf16_f32 v88, v99, v104
	s_nop 1
	v_cndmask_b32_e32 v91, v89, v93, vcc
	v_cvt_pk_bf16_f32 v89, v102, v103
	v_cvt_pk_bf16_f32 v91, v92, v91
	flat_store_dwordx4 v[96:97], v[88:91]
	v_pk_mul_f32 v[92:93], v[84:85], v[84:85]
	v_cmp_gt_f32_e32 vcc, 0, v84
	v_and_b32_e32 v89, 0x7fffffff, v85
	v_and_b32_e32 v88, 0x7fffffff, v84
	v_pk_fma_f32 v[88:89], v[88:89], s[36:37], 1.0 op_sel_hi:[1,0,0]
	v_pk_mul_f32 v[92:93], v[92:93], s[58:59] op_sel_hi:[1,0]
	v_rcp_f32_e32 v88, v88
	v_rcp_f32_e32 v89, v89
	v_exp_f32_e32 v92, v92
	v_exp_f32_e32 v93, v93
	v_pk_fma_f32 v[90:91], v[88:89], s[12:13], v[120:121] op_sel_hi:[1,0,0]
	s_nop 0
	v_pk_fma_f32 v[90:91], v[88:89], v[90:91], s[8:9] op_sel_hi:[1,1,0]
	s_nop 0
	v_pk_fma_f32 v[90:91], v[88:89], v[90:91], s[24:25] op_sel_hi:[1,1,0]
	s_nop 0
	v_pk_fma_f32 v[90:91], v[88:89], v[90:91], s[56:57] op_sel_hi:[1,1,0]
	s_nop 0
	v_pk_mul_f32 v[88:89], v[88:89], v[90:91]
	v_pk_mul_f32 v[90:91], v[86:87], v[86:87]
	v_pk_mul_f32 v[88:89], v[92:93], v[88:89]
	s_nop 0
	v_pk_mul_f32 v[92:93], v[84:85], v[88:89]
	v_pk_fma_f32 v[88:89], v[84:85], v[88:89], v[84:85] neg_lo:[1,0,0] neg_hi:[1,0,0]
	v_and_b32_e32 v84, 0x7fffffff, v86
	v_cndmask_b32_e32 v92, v88, v92, vcc
	v_cmp_gt_f32_e32 vcc, 0, v85
	v_and_b32_e32 v85, 0x7fffffff, v87
	v_pk_fma_f32 v[84:85], v[84:85], s[36:37], 1.0 op_sel_hi:[1,0,0]
	v_cndmask_b32_e32 v93, v89, v93, vcc
	v_rcp_f32_e32 v84, v84
	v_rcp_f32_e32 v85, v85
	v_cmp_gt_f32_e32 vcc, 0, v86
	v_pk_fma_f32 v[88:89], v[84:85], s[12:13], v[120:121] op_sel_hi:[1,0,0]
	s_nop 0
	v_pk_fma_f32 v[88:89], v[84:85], v[88:89], s[8:9] op_sel_hi:[1,1,0]
	s_nop 0
	v_pk_fma_f32 v[88:89], v[84:85], v[88:89], s[24:25] op_sel_hi:[1,1,0]
	s_nop 0
	v_pk_fma_f32 v[88:89], v[84:85], v[88:89], s[56:57] op_sel_hi:[1,1,0]
	s_nop 0
	v_pk_mul_f32 v[84:85], v[84:85], v[88:89]
	v_pk_mul_f32 v[88:89], v[90:91], s[58:59] op_sel_hi:[1,0]
	s_nop 0
	v_exp_f32_e32 v88, v88
	v_exp_f32_e32 v89, v89
	s_nop 0
	v_pk_mul_f32 v[84:85], v[88:89], v[84:85]
	s_nop 0
	v_pk_mul_f32 v[88:89], v[86:87], v[84:85]
	v_pk_fma_f32 v[84:85], v[86:87], v[84:85], v[86:87] neg_lo:[1,0,0] neg_hi:[1,0,0]
	s_nop 0
	v_cndmask_b32_e32 v90, v84, v88, vcc
	v_cmp_gt_f32_e32 vcc, 0, v87
	v_and_b32_e32 v84, 0x7fffffff, v80
	s_nop 0
	v_cndmask_b32_e32 v91, v85, v89, vcc
	v_and_b32_e32 v85, 0x7fffffff, v81
	v_pk_fma_f32 v[84:85], v[84:85], s[36:37], 1.0 op_sel_hi:[1,0,0]
	v_pk_mul_f32 v[88:89], v[80:81], v[80:81]
	v_rcp_f32_e32 v84, v84
	v_rcp_f32_e32 v85, v85
	v_pk_mul_f32 v[88:89], v[88:89], s[58:59] op_sel_hi:[1,0]
	v_cmp_gt_f32_e32 vcc, 0, v80
	v_exp_f32_e32 v88, v88
	v_pk_fma_f32 v[86:87], v[84:85], s[12:13], v[120:121] op_sel_hi:[1,0,0]
	v_exp_f32_e32 v89, v89
	v_pk_fma_f32 v[86:87], v[84:85], v[86:87], s[8:9] op_sel_hi:[1,1,0]
; __device__ __forceinline__ unsigned pkbf(float lo, float hi) { unsigned r; asm("v_cvt_pk_bf16_f32 %0, %1, %2" : "=v"(r) : "v"(lo), "v"(hi)); return r; }
; __device__ __forceinline__ f32x2 gelu_pk(f32x2 v) {
;     const f32x2 av = __builtin_elementwise_abs(v), d = av * 0.2316418882f + 1.0f;
;     f32x2 t; t.x = __builtin_amdgcn_rcpf(d.x); t.y = __builtin_amdgcn_rcpf(d.y);
;     f32x2 q = t * 0.5307027145f + (-0.7265760135f); q = q * t + 0.7107068705f; q = q * t + (-0.142248368f); q = q * t + 0.127414796f; q = q * t;
;     const f32x2 s = (v * v) * (-0.72134752044f);
;     f32x2 e; e.x = __builtin_amdgcn_exp2f(s.x); e.y = __builtin_amdgcn_exp2f(s.y);
;     const f32x2 m = v * (q * e), r = v - m;
;     f32x2 o; o.x = v.x < 0.f ? m.x : r.x; o.y = v.y < 0.f ? m.y : r.y; return o;
; }
;     __device__ __forceinline__ void operator()(const f32x4 (&acc)[2][2][4][2], const Unit& u, int wr, int wc, int fr, int fq) const {
;     ...
;                 for (int m = 0; m < 4; ++m) { const int row = row0 + ai * HALF + m * 16; const float rs = rinv[row]; bf16_t* rowp = base + (size_t)row * 512;
; #pragma unroll
;                     for (int bj = 0; bj < 2; ++bj) { f32x4 v0 = acc[ai][bj][m][0] * rs, v1 = acc[ai][bj][m][1] * rs;
;                         f32x2 a = gelu_pk((f32x2){v0[0], v0[1]}), b = gelu_pk((f32x2){v0[2], v0[3]}), c = gelu_pk((f32x2){v1[0], v1[1]}), d = gelu_pk((f32x2){v1[2], v1[3]});
;                         u32x4 w; w.x = pkbf(a.x, a.y); w.y = pkbf(b.x, b.y); w.z = pkbf(c.x, c.y); w.w = pkbf(d.x, d.y);
;                         *(u32x4*)(rowp + bj * HALF) = w; } }
	s_nop 0
	v_pk_fma_f32 v[86:87], v[84:85], v[86:87], s[24:25] op_sel_hi:[1,1,0]
	s_nop 0
	v_pk_fma_f32 v[86:87], v[84:85], v[86:87], s[56:57] op_sel_hi:[1,1,0]
	s_nop 0
	v_pk_mul_f32 v[84:85], v[84:85], v[86:87]
	v_pk_mul_f32 v[86:87], v[82:83], v[82:83]
	v_pk_mul_f32 v[84:85], v[88:89], v[84:85]
	s_nop 0
	v_pk_mul_f32 v[88:89], v[80:81], v[84:85]
	v_pk_fma_f32 v[84:85], v[80:81], v[84:85], v[80:81] neg_lo:[1,0,0] neg_hi:[1,0,0]
	v_and_b32_e32 v80, 0x7fffffff, v82
	v_cndmask_b32_e32 v88, v84, v88, vcc
	v_cmp_gt_f32_e32 vcc, 0, v81
	v_and_b32_e32 v81, 0x7fffffff, v83
	v_pk_fma_f32 v[80:81], v[80:81], s[36:37], 1.0 op_sel_hi:[1,0,0]
	v_cndmask_b32_e32 v89, v85, v89, vcc
	v_rcp_f32_e32 v80, v80
	v_rcp_f32_e32 v81, v81
	v_cmp_gt_f32_e32 vcc, 0, v82
	v_pk_fma_f32 v[84:85], v[80:81], s[12:13], v[120:121] op_sel_hi:[1,0,0]
	s_nop 0
	v_pk_fma_f32 v[84:85], v[80:81], v[84:85], s[8:9] op_sel_hi:[1,1,0]
	s_nop 0
	v_pk_fma_f32 v[84:85], v[80:81], v[84:85], s[24:25] op_sel_hi:[1,1,0]
	s_nop 0
	v_pk_fma_f32 v[84:85], v[80:81], v[84:85], s[56:57] op_sel_hi:[1,1,0]
	s_nop 0
	v_pk_mul_f32 v[80:81], v[80:81], v[84:85]
	v_pk_mul_f32 v[84:85], v[86:87], s[58:59] op_sel_hi:[1,0]
	s_nop 0
	v_exp_f32_e32 v84, v84
	v_exp_f32_e32 v85, v85
	s_nop 0
	v_pk_mul_f32 v[80:81], v[84:85], v[80:81]
	s_nop 0
	v_pk_mul_f32 v[84:85], v[82:83], v[80:81]
	v_pk_fma_f32 v[80:81], v[82:83], v[80:81], v[82:83] neg_lo:[1,0,0] neg_hi:[1,0,0]
	v_cvt_pk_bf16_f32 v82, v88, v89
	s_nop 0
	v_cndmask_b32_e32 v84, v80, v84, vcc
	v_cmp_gt_f32_e32 vcc, 0, v83
	v_cvt_pk_bf16_f32 v80, v92, v93
	s_nop 1
	v_cndmask_b32_e32 v83, v81, v85, vcc
	v_cvt_pk_bf16_f32 v81, v90, v91
	v_cvt_pk_bf16_f32 v83, v84, v83
	flat_store_dwordx4 v[96:97], v[80:83] offset:256
	s_nop 1
	v_or_b32_e32 v80, 48, v158
	v_ashrrev_i32_e32 v81, 31, v80
	v_lshl_add_u64 v[82:83], v[80:81], 2, s[40:41]
	s_nop 0
	v_lshlrev_b64 v[80:81], 10, v[80:81]
	v_lshl_add_u64 v[80:81], v[132:133], 0, v[80:81]
	s_nop 0
	v_pk_mul_f32 v[76:77], v[76:77], v[172:173] op_sel_hi:[1,0]
	s_nop 0
	v_and_b32_e32 v85, 0x7fffffff, v77
	v_and_b32_e32 v84, 0x7fffffff, v76
	v_pk_fma_f32 v[84:85], v[84:85], s[36:37], 1.0 op_sel_hi:[1,0,0]
	v_pk_mul_f32 v[88:89], v[76:77], v[76:77]
	v_rcp_f32_e32 v84, v84
	v_rcp_f32_e32 v85, v85
	v_pk_mul_f32 v[88:89], v[88:89], s[58:59] op_sel_hi:[1,0]
	v_pk_mul_f32 v[78:79], v[78:79], v[172:173] op_sel_hi:[1,0]
	v_exp_f32_e32 v88, v88
	v_pk_fma_f32 v[86:87], v[84:85], s[12:13], v[120:121] op_sel_hi:[1,0,0]
	v_exp_f32_e32 v89, v89
	v_pk_fma_f32 v[86:87], v[84:85], v[86:87], s[8:9] op_sel_hi:[1,1,0]
	v_cmp_gt_f32_e32 vcc, 0, v76
	v_pk_fma_f32 v[86:87], v[84:85], v[86:87], s[24:25] op_sel_hi:[1,1,0]
	v_pk_mul_f32 v[74:75], v[74:75], v[172:173] op_sel_hi:[1,0]
	v_pk_fma_f32 v[86:87], v[84:85], v[86:87], s[56:57] op_sel_hi:[1,1,0]
	v_pk_mul_f32 v[72:73], v[72:73], v[172:173] op_sel_hi:[1,0]
	v_pk_mul_f32 v[84:85], v[84:85], v[86:87]
	v_pk_mul_f32 v[86:87], v[78:79], v[78:79]
	v_pk_mul_f32 v[84:85], v[88:89], v[84:85]
	s_nop 0
	v_pk_mul_f32 v[88:89], v[76:77], v[84:85]
	v_pk_fma_f32 v[84:85], v[76:77], v[84:85], v[76:77] neg_lo:[1,0,0] neg_hi:[1,0,0]
	v_and_b32_e32 v76, 0x7fffffff, v78
	v_cndmask_b32_e32 v83, v84, v88, vcc
	v_cmp_gt_f32_e32 vcc, 0, v77
	v_and_b32_e32 v77, 0x7fffffff, v79
	v_pk_fma_f32 v[76:77], v[76:77], s[36:37], 1.0 op_sel_hi:[1,0,0]
	v_cndmask_b32_e32 v88, v85, v89, vcc
	v_rcp_f32_e32 v76, v76
	v_rcp_f32_e32 v77, v77
	v_cmp_gt_f32_e32 vcc, 0, v78
	v_pk_mul_f32 v[68:69], v[68:69], v[172:173] op_sel_hi:[1,0]
	v_pk_mul_f32 v[70:71], v[70:71], v[172:173] op_sel_hi:[1,0]
	v_pk_fma_f32 v[84:85], v[76:77], s[12:13], v[120:121] op_sel_hi:[1,0,0]
	v_pk_mul_f32 v[64:65], v[64:65], v[172:173] op_sel_hi:[1,0]
	v_pk_fma_f32 v[84:85], v[76:77], v[84:85], s[8:9] op_sel_hi:[1,1,0]
	v_pk_mul_f32 v[66:67], v[66:67], v[172:173] op_sel_hi:[1,0]
	v_pk_fma_f32 v[84:85], v[76:77], v[84:85], s[24:25] op_sel_hi:[1,1,0]
	s_nop 0
	v_pk_fma_f32 v[84:85], v[76:77], v[84:85], s[56:57] op_sel_hi:[1,1,0]
	s_nop 0
	v_pk_mul_f32 v[76:77], v[76:77], v[84:85]
	v_pk_mul_f32 v[84:85], v[86:87], s[58:59] op_sel_hi:[1,0]
	s_nop 0
	v_exp_f32_e32 v84, v84
	v_exp_f32_e32 v85, v85
	s_nop 0
	v_pk_mul_f32 v[76:77], v[84:85], v[76:77]
	s_nop 0
	v_pk_mul_f32 v[84:85], v[78:79], v[76:77]
	v_pk_fma_f32 v[76:77], v[78:79], v[76:77], v[78:79] neg_lo:[1,0,0] neg_hi:[1,0,0]
	s_nop 0
	v_cndmask_b32_e32 v86, v76, v84, vcc
	v_cmp_gt_f32_e32 vcc, 0, v79
	v_and_b32_e32 v76, 0x7fffffff, v72
	s_nop 0
	v_cndmask_b32_e32 v87, v77, v85, vcc
	v_and_b32_e32 v77, 0x7fffffff, v73
	v_pk_fma_f32 v[76:77], v[76:77], s[36:37], 1.0 op_sel_hi:[1,0,0]
	v_pk_mul_f32 v[84:85], v[72:73], v[72:73]
	v_rcp_f32_e32 v76, v76
	v_rcp_f32_e32 v77, v77
	v_pk_mul_f32 v[84:85], v[84:85], s[58:59] op_sel_hi:[1,0]
	v_cmp_gt_f32_e32 vcc, 0, v72
	v_exp_f32_e32 v84, v84
	v_pk_fma_f32 v[78:79], v[76:77], s[12:13], v[120:121] op_sel_hi:[1,0,0]
	v_exp_f32_e32 v85, v85
	v_pk_fma_f32 v[78:79], v[76:77], v[78:79], s[8:9] op_sel_hi:[1,1,0]
	s_nop 0
	v_pk_fma_f32 v[78:79], v[76:77], v[78:79], s[24:25] op_sel_hi:[1,1,0]
	s_nop 0
	v_pk_fma_f32 v[78:79], v[76:77], v[78:79], s[56:57] op_sel_hi:[1,1,0]
	s_nop 0
	v_pk_mul_f32 v[76:77], v[76:77], v[78:79]
	v_pk_mul_f32 v[78:79], v[74:75], v[74:75]
	v_pk_mul_f32 v[76:77], v[84:85], v[76:77]
	s_nop 0
	v_pk_mul_f32 v[84:85], v[72:73], v[76:77]
	v_pk_fma_f32 v[76:77], v[72:73], v[76:77], v[72:73] neg_lo:[1,0,0] neg_hi:[1,0,0]
	v_and_b32_e32 v72, 0x7fffffff, v74
	v_cndmask_b32_e32 v84, v76, v84, vcc
	v_cmp_gt_f32_e32 vcc, 0, v73
	v_and_b32_e32 v73, 0x7fffffff, v75
	v_pk_fma_f32 v[72:73], v[72:73], s[36:37], 1.0 op_sel_hi:[1,0,0]
	v_cndmask_b32_e32 v85, v77, v85, vcc
; __device__ __forceinline__ unsigned pkbf(float lo, float hi) { unsigned r; asm("v_cvt_pk_bf16_f32 %0, %1, %2" : "=v"(r) : "v"(lo), "v"(hi)); return r; }
; __device__ __forceinline__ f32x2 gelu_pk(f32x2 v) {
;     const f32x2 av = __builtin_elementwise_abs(v), d = av * 0.2316418882f + 1.0f;
;     f32x2 t; t.x = __builtin_amdgcn_rcpf(d.x); t.y = __builtin_amdgcn_rcpf(d.y);
;     f32x2 q = t * 0.5307027145f + (-0.7265760135f); q = q * t + 0.7107068705f; q = q * t + (-0.142248368f); q = q * t + 0.127414796f; q = q * t;
;     const f32x2 s = (v * v) * (-0.72134752044f);
;     f32x2 e; e.x = __builtin_amdgcn_exp2f(s.x); e.y = __builtin_amdgcn_exp2f(s.y);
;     const f32x2 m = v * (q * e), r = v - m;
;     f32x2 o; o.x = v.x < 0.f ? m.x : r.x; o.y = v.y < 0.f ? m.y : r.y; return o;
; }
;     __device__ __forceinline__ void operator()(const f32x4 (&acc)[2][2][4][2], const Unit& u, int wr, int wc, int fr, int fq) const {
;     ...
;                 for (int m = 0; m < 4; ++m) { const int row = row0 + ai * HALF + m * 16; const float rs = rinv[row]; bf16_t* rowp = base + (size_t)row * 512;
; #pragma unroll
;                     for (int bj = 0; bj < 2; ++bj) { f32x4 v0 = acc[ai][bj][m][0] * rs, v1 = acc[ai][bj][m][1] * rs;
;                         f32x2 a = gelu_pk((f32x2){v0[0], v0[1]}), b = gelu_pk((f32x2){v0[2], v0[3]}), c = gelu_pk((f32x2){v1[0], v1[1]}), d = gelu_pk((f32x2){v1[2], v1[3]});
;                         u32x4 w; w.x = pkbf(a.x, a.y); w.y = pkbf(b.x, b.y); w.z = pkbf(c.x, c.y); w.w = pkbf(d.x, d.y);
;                         *(u32x4*)(rowp + bj * HALF) = w; } }
	v_rcp_f32_e32 v72, v72
	v_rcp_f32_e32 v73, v73
	v_cmp_gt_f32_e32 vcc, 0, v74
	v_pk_fma_f32 v[76:77], v[72:73], s[12:13], v[120:121] op_sel_hi:[1,0,0]
	s_nop 0
	v_pk_fma_f32 v[76:77], v[72:73], v[76:77], s[8:9] op_sel_hi:[1,1,0]
	s_nop 0
	v_pk_fma_f32 v[76:77], v[72:73], v[76:77], s[24:25] op_sel_hi:[1,1,0]
	s_nop 0
	v_pk_fma_f32 v[76:77], v[72:73], v[76:77], s[56:57] op_sel_hi:[1,1,0]
	s_nop 0
	v_pk_mul_f32 v[72:73], v[72:73], v[76:77]
	v_pk_mul_f32 v[76:77], v[78:79], s[58:59] op_sel_hi:[1,0]
	s_nop 0
	v_exp_f32_e32 v76, v76
	v_exp_f32_e32 v77, v77
	s_nop 0
	v_pk_mul_f32 v[72:73], v[76:77], v[72:73]
	s_nop 0
	v_pk_mul_f32 v[76:77], v[74:75], v[72:73]
	v_pk_fma_f32 v[72:73], v[74:75], v[72:73], v[74:75] neg_lo:[1,0,0] neg_hi:[1,0,0]
	v_cvt_pk_bf16_f32 v74, v84, v85
	s_nop 0
	v_cndmask_b32_e32 v76, v72, v76, vcc
	v_cmp_gt_f32_e32 vcc, 0, v75
	v_cvt_pk_bf16_f32 v72, v83, v88
	s_nop 1
	v_cndmask_b32_e32 v75, v73, v77, vcc
	v_cvt_pk_bf16_f32 v73, v86, v87
	v_cvt_pk_bf16_f32 v75, v76, v75
	flat_store_dwordx4 v[80:81], v[72:75]
	v_pk_mul_f32 v[76:77], v[68:69], v[68:69]
	v_cmp_gt_f32_e32 vcc, 0, v68
	v_and_b32_e32 v73, 0x7fffffff, v69
	v_and_b32_e32 v72, 0x7fffffff, v68
	v_pk_fma_f32 v[72:73], v[72:73], s[36:37], 1.0 op_sel_hi:[1,0,0]
	v_pk_mul_f32 v[76:77], v[76:77], s[58:59] op_sel_hi:[1,0]
	v_rcp_f32_e32 v72, v72
	v_rcp_f32_e32 v73, v73
	v_exp_f32_e32 v76, v76
	v_exp_f32_e32 v77, v77
	v_pk_fma_f32 v[74:75], v[72:73], s[12:13], v[120:121] op_sel_hi:[1,0,0]
	s_nop 0
	v_pk_fma_f32 v[74:75], v[72:73], v[74:75], s[8:9] op_sel_hi:[1,1,0]
	s_nop 0
	v_pk_fma_f32 v[74:75], v[72:73], v[74:75], s[24:25] op_sel_hi:[1,1,0]
	s_nop 0
	v_pk_fma_f32 v[74:75], v[72:73], v[74:75], s[56:57] op_sel_hi:[1,1,0]
	s_nop 0
	v_pk_mul_f32 v[72:73], v[72:73], v[74:75]
	v_pk_mul_f32 v[74:75], v[70:71], v[70:71]
	v_pk_mul_f32 v[72:73], v[76:77], v[72:73]
	s_nop 0
	v_pk_mul_f32 v[76:77], v[68:69], v[72:73]
	v_pk_fma_f32 v[72:73], v[68:69], v[72:73], v[68:69] neg_lo:[1,0,0] neg_hi:[1,0,0]
	v_and_b32_e32 v68, 0x7fffffff, v70
	v_cndmask_b32_e32 v76, v72, v76, vcc
	v_cmp_gt_f32_e32 vcc, 0, v69
	v_and_b32_e32 v69, 0x7fffffff, v71
	v_pk_fma_f32 v[68:69], v[68:69], s[36:37], 1.0 op_sel_hi:[1,0,0]
	v_cndmask_b32_e32 v77, v73, v77, vcc
	v_rcp_f32_e32 v68, v68
	v_rcp_f32_e32 v69, v69
	v_cmp_gt_f32_e32 vcc, 0, v70
	v_pk_fma_f32 v[72:73], v[68:69], s[12:13], v[120:121] op_sel_hi:[1,0,0]
	s_nop 0
	v_pk_fma_f32 v[72:73], v[68:69], v[72:73], s[8:9] op_sel_hi:[1,1,0]
	s_nop 0
	v_pk_fma_f32 v[72:73], v[68:69], v[72:73], s[24:25] op_sel_hi:[1,1,0]
	s_nop 0
	v_pk_fma_f32 v[72:73], v[68:69], v[72:73], s[56:57] op_sel_hi:[1,1,0]
	s_nop 0
	v_pk_mul_f32 v[68:69], v[68:69], v[72:73]
	v_pk_mul_f32 v[72:73], v[74:75], s[58:59] op_sel_hi:[1,0]
	s_nop 0
	v_exp_f32_e32 v72, v72
	v_exp_f32_e32 v73, v73
	s_nop 0
	v_pk_mul_f32 v[68:69], v[72:73], v[68:69]
	s_nop 0
	v_pk_mul_f32 v[72:73], v[70:71], v[68:69]
	v_pk_fma_f32 v[68:69], v[70:71], v[68:69], v[70:71] neg_lo:[1,0,0] neg_hi:[1,0,0]
	s_nop 0
	v_cndmask_b32_e32 v74, v68, v72, vcc
	v_cmp_gt_f32_e32 vcc, 0, v71
	v_and_b32_e32 v68, 0x7fffffff, v64
	s_nop 0
	v_cndmask_b32_e32 v75, v69, v73, vcc
	v_and_b32_e32 v69, 0x7fffffff, v65
	v_pk_fma_f32 v[68:69], v[68:69], s[36:37], 1.0 op_sel_hi:[1,0,0]
	v_pk_mul_f32 v[72:73], v[64:65], v[64:65]
	v_rcp_f32_e32 v68, v68
	v_rcp_f32_e32 v69, v69
	v_pk_mul_f32 v[72:73], v[72:73], s[58:59] op_sel_hi:[1,0]
	v_cmp_gt_f32_e32 vcc, 0, v64
	v_exp_f32_e32 v72, v72
	v_pk_fma_f32 v[70:71], v[68:69], s[12:13], v[120:121] op_sel_hi:[1,0,0]
	v_exp_f32_e32 v73, v73
	v_pk_fma_f32 v[70:71], v[68:69], v[70:71], s[8:9] op_sel_hi:[1,1,0]
	s_nop 0
	v_pk_fma_f32 v[70:71], v[68:69], v[70:71], s[24:25] op_sel_hi:[1,1,0]
	s_nop 0
	v_pk_fma_f32 v[70:71], v[68:69], v[70:71], s[56:57] op_sel_hi:[1,1,0]
	s_nop 0
	v_pk_mul_f32 v[68:69], v[68:69], v[70:71]
	v_pk_mul_f32 v[70:71], v[66:67], v[66:67]
	v_pk_mul_f32 v[68:69], v[72:73], v[68:69]
	s_nop 0
	v_pk_mul_f32 v[72:73], v[64:65], v[68:69]
	v_pk_fma_f32 v[68:69], v[64:65], v[68:69], v[64:65] neg_lo:[1,0,0] neg_hi:[1,0,0]
	v_and_b32_e32 v64, 0x7fffffff, v66
	v_cndmask_b32_e32 v72, v68, v72, vcc
	v_cmp_gt_f32_e32 vcc, 0, v65
	v_and_b32_e32 v65, 0x7fffffff, v67
	v_pk_fma_f32 v[64:65], v[64:65], s[36:37], 1.0 op_sel_hi:[1,0,0]
	v_cndmask_b32_e32 v73, v69, v73, vcc
	v_rcp_f32_e32 v64, v64
	v_rcp_f32_e32 v65, v65
	v_cmp_gt_f32_e32 vcc, 0, v66
	v_pk_fma_f32 v[68:69], v[64:65], s[12:13], v[120:121] op_sel_hi:[1,0,0]
	s_nop 0
	v_pk_fma_f32 v[68:69], v[64:65], v[68:69], s[8:9] op_sel_hi:[1,1,0]
	s_nop 0
	v_pk_fma_f32 v[68:69], v[64:65], v[68:69], s[24:25] op_sel_hi:[1,1,0]
	s_nop 0
	v_pk_fma_f32 v[68:69], v[64:65], v[68:69], s[56:57] op_sel_hi:[1,1,0]
	s_nop 0
	v_pk_mul_f32 v[64:65], v[64:65], v[68:69]
	v_pk_mul_f32 v[68:69], v[70:71], s[58:59] op_sel_hi:[1,0]
	s_nop 0
	v_exp_f32_e32 v68, v68
	v_exp_f32_e32 v69, v69
	s_nop 0
	v_pk_mul_f32 v[64:65], v[68:69], v[64:65]
	s_nop 0
	v_pk_mul_f32 v[68:69], v[66:67], v[64:65]
	v_pk_fma_f32 v[64:65], v[66:67], v[64:65], v[66:67] neg_lo:[1,0,0] neg_hi:[1,0,0]
	v_cvt_pk_bf16_f32 v66, v72, v73
	s_nop 0
	v_cndmask_b32_e32 v68, v64, v68, vcc
	v_cmp_gt_f32_e32 vcc, 0, v67
	v_cvt_pk_bf16_f32 v64, v76, v77
	s_nop 1
	v_cndmask_b32_e32 v67, v65, v69, vcc
	v_cvt_pk_bf16_f32 v65, v74, v75
	v_cvt_pk_bf16_f32 v67, v68, v67
	flat_store_dwordx4 v[80:81], v[64:67] offset:256
	s_nop 0
	s_nop 0
	v_pk_mul_f32 v[60:61], v[60:61], v[174:175] op_sel_hi:[1,0]
	s_nop 0
	v_and_b32_e32 v69, 0x7fffffff, v61
	v_and_b32_e32 v68, 0x7fffffff, v60
	v_pk_fma_f32 v[68:69], v[68:69], s[36:37], 1.0 op_sel_hi:[1,0,0]
	v_pk_mul_f32 v[72:73], v[60:61], v[60:61]
	v_rcp_f32_e32 v68, v68
; __device__ __forceinline__ unsigned pkbf(float lo, float hi) { unsigned r; asm("v_cvt_pk_bf16_f32 %0, %1, %2" : "=v"(r) : "v"(lo), "v"(hi)); return r; }
; __device__ __forceinline__ f32x2 gelu_pk(f32x2 v) {
;     const f32x2 av = __builtin_elementwise_abs(v), d = av * 0.2316418882f + 1.0f;
;     f32x2 t; t.x = __builtin_amdgcn_rcpf(d.x); t.y = __builtin_amdgcn_rcpf(d.y);
;     f32x2 q = t * 0.5307027145f + (-0.7265760135f); q = q * t + 0.7107068705f; q = q * t + (-0.142248368f); q = q * t + 0.127414796f; q = q * t;
;     const f32x2 s = (v * v) * (-0.72134752044f);
;     f32x2 e; e.x = __builtin_amdgcn_exp2f(s.x); e.y = __builtin_amdgcn_exp2f(s.y);
;     const f32x2 m = v * (q * e), r = v - m;
;     f32x2 o; o.x = v.x < 0.f ? m.x : r.x; o.y = v.y < 0.f ? m.y : r.y; return o;
; }
;     __device__ __forceinline__ void operator()(const f32x4 (&acc)[2][2][4][2], const Unit& u, int wr, int wc, int fr, int fq) const {
;     ...
;                 for (int m = 0; m < 4; ++m) { const int row = row0 + ai * HALF + m * 16; const float rs = rinv[row]; bf16_t* rowp = base + (size_t)row * 512;
; #pragma unroll
;                     for (int bj = 0; bj < 2; ++bj) { f32x4 v0 = acc[ai][bj][m][0] * rs, v1 = acc[ai][bj][m][1] * rs;
;                         f32x2 a = gelu_pk((f32x2){v0[0], v0[1]}), b = gelu_pk((f32x2){v0[2], v0[3]}), c = gelu_pk((f32x2){v1[0], v1[1]}), d = gelu_pk((f32x2){v1[2], v1[3]});
;                         u32x4 w; w.x = pkbf(a.x, a.y); w.y = pkbf(b.x, b.y); w.z = pkbf(c.x, c.y); w.w = pkbf(d.x, d.y);
;                         *(u32x4*)(rowp + bj * HALF) = w; } }
	v_rcp_f32_e32 v69, v69
	v_pk_mul_f32 v[72:73], v[72:73], s[58:59] op_sel_hi:[1,0]
	v_pk_mul_f32 v[62:63], v[62:63], v[174:175] op_sel_hi:[1,0]
	v_exp_f32_e32 v72, v72
	v_pk_fma_f32 v[70:71], v[68:69], s[12:13], v[120:121] op_sel_hi:[1,0,0]
	v_exp_f32_e32 v73, v73
	v_pk_fma_f32 v[70:71], v[68:69], v[70:71], s[8:9] op_sel_hi:[1,1,0]
	v_cmp_gt_f32_e32 vcc, 0, v60
	v_pk_fma_f32 v[70:71], v[68:69], v[70:71], s[24:25] op_sel_hi:[1,1,0]
	v_pk_mul_f32 v[58:59], v[58:59], v[174:175] op_sel_hi:[1,0]
	v_pk_fma_f32 v[70:71], v[68:69], v[70:71], s[56:57] op_sel_hi:[1,1,0]
	v_pk_mul_f32 v[56:57], v[56:57], v[174:175] op_sel_hi:[1,0]
	v_pk_mul_f32 v[68:69], v[68:69], v[70:71]
	v_pk_mul_f32 v[70:71], v[62:63], v[62:63]
	v_pk_mul_f32 v[68:69], v[72:73], v[68:69]
	v_lshl_add_u64 v[64:65], v[128:129], 0, s[60:61]
	v_pk_mul_f32 v[72:73], v[60:61], v[68:69]
	v_pk_fma_f32 v[68:69], v[60:61], v[68:69], v[60:61] neg_lo:[1,0,0] neg_hi:[1,0,0]
	v_and_b32_e32 v60, 0x7fffffff, v62
	v_cndmask_b32_e32 v67, v68, v72, vcc
	v_cmp_gt_f32_e32 vcc, 0, v61
	v_and_b32_e32 v61, 0x7fffffff, v63
	v_pk_fma_f32 v[60:61], v[60:61], s[36:37], 1.0 op_sel_hi:[1,0,0]
	v_cndmask_b32_e32 v72, v69, v73, vcc
	v_rcp_f32_e32 v60, v60
	v_rcp_f32_e32 v61, v61
	v_cmp_gt_f32_e32 vcc, 0, v62
	v_pk_mul_f32 v[52:53], v[52:53], v[174:175] op_sel_hi:[1,0]
	v_pk_mul_f32 v[54:55], v[54:55], v[174:175] op_sel_hi:[1,0]
	v_pk_fma_f32 v[68:69], v[60:61], s[12:13], v[120:121] op_sel_hi:[1,0,0]
	v_pk_mul_f32 v[48:49], v[48:49], v[174:175] op_sel_hi:[1,0]
	v_pk_fma_f32 v[68:69], v[60:61], v[68:69], s[8:9] op_sel_hi:[1,1,0]
	v_pk_mul_f32 v[50:51], v[50:51], v[174:175] op_sel_hi:[1,0]
	v_pk_fma_f32 v[68:69], v[60:61], v[68:69], s[24:25] op_sel_hi:[1,1,0]
	s_nop 0
	v_pk_fma_f32 v[68:69], v[60:61], v[68:69], s[56:57] op_sel_hi:[1,1,0]
	s_nop 0
	v_pk_mul_f32 v[60:61], v[60:61], v[68:69]
	v_pk_mul_f32 v[68:69], v[70:71], s[58:59] op_sel_hi:[1,0]
	s_nop 0
	v_exp_f32_e32 v68, v68
	v_exp_f32_e32 v69, v69
	s_nop 0
	v_pk_mul_f32 v[60:61], v[68:69], v[60:61]
	s_nop 0
	v_pk_mul_f32 v[68:69], v[62:63], v[60:61]
	v_pk_fma_f32 v[60:61], v[62:63], v[60:61], v[62:63] neg_lo:[1,0,0] neg_hi:[1,0,0]
	s_nop 0
	v_cndmask_b32_e32 v70, v60, v68, vcc
	v_cmp_gt_f32_e32 vcc, 0, v63
	v_and_b32_e32 v60, 0x7fffffff, v56
	s_nop 0
	v_cndmask_b32_e32 v71, v61, v69, vcc
	v_and_b32_e32 v61, 0x7fffffff, v57
	v_pk_fma_f32 v[60:61], v[60:61], s[36:37], 1.0 op_sel_hi:[1,0,0]
	v_pk_mul_f32 v[68:69], v[56:57], v[56:57]
	v_rcp_f32_e32 v60, v60
	v_rcp_f32_e32 v61, v61
	v_pk_mul_f32 v[68:69], v[68:69], s[58:59] op_sel_hi:[1,0]
	v_cmp_gt_f32_e32 vcc, 0, v56
	v_exp_f32_e32 v68, v68
	v_pk_fma_f32 v[62:63], v[60:61], s[12:13], v[120:121] op_sel_hi:[1,0,0]
	v_exp_f32_e32 v69, v69
	v_pk_fma_f32 v[62:63], v[60:61], v[62:63], s[8:9] op_sel_hi:[1,1,0]
	s_nop 0
	v_pk_fma_f32 v[62:63], v[60:61], v[62:63], s[24:25] op_sel_hi:[1,1,0]
	s_nop 0
	v_pk_fma_f32 v[62:63], v[60:61], v[62:63], s[56:57] op_sel_hi:[1,1,0]
	s_nop 0
	v_pk_mul_f32 v[60:61], v[60:61], v[62:63]
	v_pk_mul_f32 v[62:63], v[58:59], v[58:59]
	v_pk_mul_f32 v[60:61], v[68:69], v[60:61]
	s_nop 0
	v_pk_mul_f32 v[68:69], v[56:57], v[60:61]
	v_pk_fma_f32 v[60:61], v[56:57], v[60:61], v[56:57] neg_lo:[1,0,0] neg_hi:[1,0,0]
	v_and_b32_e32 v56, 0x7fffffff, v58
	v_cndmask_b32_e32 v68, v60, v68, vcc
	v_cmp_gt_f32_e32 vcc, 0, v57
	v_and_b32_e32 v57, 0x7fffffff, v59
	v_pk_fma_f32 v[56:57], v[56:57], s[36:37], 1.0 op_sel_hi:[1,0,0]
	v_cndmask_b32_e32 v69, v61, v69, vcc
	v_rcp_f32_e32 v56, v56
	v_rcp_f32_e32 v57, v57
	v_cmp_gt_f32_e32 vcc, 0, v58
	v_pk_fma_f32 v[60:61], v[56:57], s[12:13], v[120:121] op_sel_hi:[1,0,0]
	s_nop 0
	v_pk_fma_f32 v[60:61], v[56:57], v[60:61], s[8:9] op_sel_hi:[1,1,0]
	s_nop 0
	v_pk_fma_f32 v[60:61], v[56:57], v[60:61], s[24:25] op_sel_hi:[1,1,0]
	s_nop 0
	v_pk_fma_f32 v[60:61], v[56:57], v[60:61], s[56:57] op_sel_hi:[1,1,0]
	s_nop 0
	v_pk_mul_f32 v[56:57], v[56:57], v[60:61]
	v_pk_mul_f32 v[60:61], v[62:63], s[58:59] op_sel_hi:[1,0]
	s_nop 0
	v_exp_f32_e32 v60, v60
	v_exp_f32_e32 v61, v61
	s_nop 0
	v_pk_mul_f32 v[56:57], v[60:61], v[56:57]
	s_nop 0
	v_pk_mul_f32 v[60:61], v[58:59], v[56:57]
	v_pk_fma_f32 v[56:57], v[58:59], v[56:57], v[58:59] neg_lo:[1,0,0] neg_hi:[1,0,0]
	v_cvt_pk_bf16_f32 v58, v68, v69
	s_nop 0
	v_cndmask_b32_e32 v60, v56, v60, vcc
	v_cmp_gt_f32_e32 vcc, 0, v59
	v_cvt_pk_bf16_f32 v56, v67, v72
	s_nop 1
	v_cndmask_b32_e32 v59, v57, v61, vcc
	v_cvt_pk_bf16_f32 v59, v60, v59
	v_add_co_u32_e32 v60, vcc, s10, v128
	v_cvt_pk_bf16_f32 v57, v70, v71
	s_mov_b64 s[10:11], 0x24000
	s_nop 0
	v_addc_co_u32_e32 v61, vcc, 0, v129, vcc
	flat_store_dwordx4 v[60:61], v[56:59]
	v_pk_mul_f32 v[60:61], v[52:53], v[52:53]
	v_cmp_gt_f32_e32 vcc, 0, v52
	v_and_b32_e32 v57, 0x7fffffff, v53
	v_and_b32_e32 v56, 0x7fffffff, v52
	v_pk_fma_f32 v[56:57], v[56:57], s[36:37], 1.0 op_sel_hi:[1,0,0]
	v_pk_mul_f32 v[60:61], v[60:61], s[58:59] op_sel_hi:[1,0]
	v_rcp_f32_e32 v56, v56
	v_rcp_f32_e32 v57, v57
	v_exp_f32_e32 v60, v60
	v_exp_f32_e32 v61, v61
	v_pk_fma_f32 v[58:59], v[56:57], s[12:13], v[120:121] op_sel_hi:[1,0,0]
	s_nop 0
	v_pk_fma_f32 v[58:59], v[56:57], v[58:59], s[8:9] op_sel_hi:[1,1,0]
	s_nop 0
	v_pk_fma_f32 v[58:59], v[56:57], v[58:59], s[24:25] op_sel_hi:[1,1,0]
	s_nop 0
	v_pk_fma_f32 v[58:59], v[56:57], v[58:59], s[56:57] op_sel_hi:[1,1,0]
	s_nop 0
	v_pk_mul_f32 v[56:57], v[56:57], v[58:59]
	v_pk_mul_f32 v[58:59], v[54:55], v[54:55]
	v_pk_mul_f32 v[56:57], v[60:61], v[56:57]
	s_nop 0
	v_pk_mul_f32 v[60:61], v[52:53], v[56:57]
	v_pk_fma_f32 v[56:57], v[52:53], v[56:57], v[52:53] neg_lo:[1,0,0] neg_hi:[1,0,0]
	v_and_b32_e32 v52, 0x7fffffff, v54
	v_cndmask_b32_e32 v60, v56, v60, vcc
; __device__ __forceinline__ unsigned pkbf(float lo, float hi) { unsigned r; asm("v_cvt_pk_bf16_f32 %0, %1, %2" : "=v"(r) : "v"(lo), "v"(hi)); return r; }
; __device__ __forceinline__ f32x2 gelu_pk(f32x2 v) {
;     const f32x2 av = __builtin_elementwise_abs(v), d = av * 0.2316418882f + 1.0f;
;     f32x2 t; t.x = __builtin_amdgcn_rcpf(d.x); t.y = __builtin_amdgcn_rcpf(d.y);
;     f32x2 q = t * 0.5307027145f + (-0.7265760135f); q = q * t + 0.7107068705f; q = q * t + (-0.142248368f); q = q * t + 0.127414796f; q = q * t;
;     const f32x2 s = (v * v) * (-0.72134752044f);
;     f32x2 e; e.x = __builtin_amdgcn_exp2f(s.x); e.y = __builtin_amdgcn_exp2f(s.y);
;     const f32x2 m = v * (q * e), r = v - m;
;     f32x2 o; o.x = v.x < 0.f ? m.x : r.x; o.y = v.y < 0.f ? m.y : r.y; return o;
; }
;     __device__ __forceinline__ void operator()(const f32x4 (&acc)[2][2][4][2], const Unit& u, int wr, int wc, int fr, int fq) const {
;     ...
;                 for (int m = 0; m < 4; ++m) { const int row = row0 + ai * HALF + m * 16; const float rs = rinv[row]; bf16_t* rowp = base + (size_t)row * 512;
; #pragma unroll
;                     for (int bj = 0; bj < 2; ++bj) { f32x4 v0 = acc[ai][bj][m][0] * rs, v1 = acc[ai][bj][m][1] * rs;
;                         f32x2 a = gelu_pk((f32x2){v0[0], v0[1]}), b = gelu_pk((f32x2){v0[2], v0[3]}), c = gelu_pk((f32x2){v1[0], v1[1]}), d = gelu_pk((f32x2){v1[2], v1[3]});
;                         u32x4 w; w.x = pkbf(a.x, a.y); w.y = pkbf(b.x, b.y); w.z = pkbf(c.x, c.y); w.w = pkbf(d.x, d.y);
;                         *(u32x4*)(rowp + bj * HALF) = w; } }
	v_cmp_gt_f32_e32 vcc, 0, v53
	v_and_b32_e32 v53, 0x7fffffff, v55
	v_pk_fma_f32 v[52:53], v[52:53], s[36:37], 1.0 op_sel_hi:[1,0,0]
	v_cndmask_b32_e32 v61, v57, v61, vcc
	v_rcp_f32_e32 v52, v52
	v_rcp_f32_e32 v53, v53
	v_cmp_gt_f32_e32 vcc, 0, v54
	v_pk_fma_f32 v[56:57], v[52:53], s[12:13], v[120:121] op_sel_hi:[1,0,0]
	s_nop 0
	v_pk_fma_f32 v[56:57], v[52:53], v[56:57], s[8:9] op_sel_hi:[1,1,0]
	s_nop 0
	v_pk_fma_f32 v[56:57], v[52:53], v[56:57], s[24:25] op_sel_hi:[1,1,0]
	s_nop 0
	v_pk_fma_f32 v[56:57], v[52:53], v[56:57], s[56:57] op_sel_hi:[1,1,0]
	s_nop 0
	v_pk_mul_f32 v[52:53], v[52:53], v[56:57]
	v_pk_mul_f32 v[56:57], v[58:59], s[58:59] op_sel_hi:[1,0]
	s_nop 0
	v_exp_f32_e32 v56, v56
	v_exp_f32_e32 v57, v57
	s_nop 0
	v_pk_mul_f32 v[52:53], v[56:57], v[52:53]
	s_nop 0
	v_pk_mul_f32 v[56:57], v[54:55], v[52:53]
	v_pk_fma_f32 v[52:53], v[54:55], v[52:53], v[54:55] neg_lo:[1,0,0] neg_hi:[1,0,0]
	s_nop 0
	v_cndmask_b32_e32 v58, v52, v56, vcc
	v_cmp_gt_f32_e32 vcc, 0, v55
	v_and_b32_e32 v52, 0x7fffffff, v48
	s_nop 0
	v_cndmask_b32_e32 v59, v53, v57, vcc
	v_and_b32_e32 v53, 0x7fffffff, v49
	v_pk_fma_f32 v[52:53], v[52:53], s[36:37], 1.0 op_sel_hi:[1,0,0]
	v_pk_mul_f32 v[56:57], v[48:49], v[48:49]
	v_rcp_f32_e32 v52, v52
	v_rcp_f32_e32 v53, v53
	v_pk_mul_f32 v[56:57], v[56:57], s[58:59] op_sel_hi:[1,0]
	v_cmp_gt_f32_e32 vcc, 0, v48
	v_exp_f32_e32 v56, v56
	v_pk_fma_f32 v[54:55], v[52:53], s[12:13], v[120:121] op_sel_hi:[1,0,0]
	v_exp_f32_e32 v57, v57
	v_pk_fma_f32 v[54:55], v[52:53], v[54:55], s[8:9] op_sel_hi:[1,1,0]
	s_nop 0
	v_pk_fma_f32 v[54:55], v[52:53], v[54:55], s[24:25] op_sel_hi:[1,1,0]
	s_nop 0
	v_pk_fma_f32 v[54:55], v[52:53], v[54:55], s[56:57] op_sel_hi:[1,1,0]
	s_nop 0
	v_pk_mul_f32 v[52:53], v[52:53], v[54:55]
	v_pk_mul_f32 v[54:55], v[50:51], v[50:51]
	v_pk_mul_f32 v[52:53], v[56:57], v[52:53]
	s_nop 0
	v_pk_mul_f32 v[56:57], v[48:49], v[52:53]
	v_pk_fma_f32 v[52:53], v[48:49], v[52:53], v[48:49] neg_lo:[1,0,0] neg_hi:[1,0,0]
	v_and_b32_e32 v48, 0x7fffffff, v50
	v_cndmask_b32_e32 v56, v52, v56, vcc
	v_cmp_gt_f32_e32 vcc, 0, v49
	v_and_b32_e32 v49, 0x7fffffff, v51
	v_pk_fma_f32 v[48:49], v[48:49], s[36:37], 1.0 op_sel_hi:[1,0,0]
	v_cndmask_b32_e32 v57, v53, v57, vcc
	v_rcp_f32_e32 v48, v48
	v_rcp_f32_e32 v49, v49
	v_cmp_gt_f32_e32 vcc, 0, v50
	v_pk_fma_f32 v[52:53], v[48:49], s[12:13], v[120:121] op_sel_hi:[1,0,0]
	s_nop 0
	v_pk_fma_f32 v[52:53], v[48:49], v[52:53], s[8:9] op_sel_hi:[1,1,0]
	s_nop 0
	v_pk_fma_f32 v[52:53], v[48:49], v[52:53], s[24:25] op_sel_hi:[1,1,0]
	s_nop 0
	v_pk_fma_f32 v[52:53], v[48:49], v[52:53], s[56:57] op_sel_hi:[1,1,0]
	s_nop 0
	v_pk_mul_f32 v[48:49], v[48:49], v[52:53]
	v_pk_mul_f32 v[52:53], v[54:55], s[58:59] op_sel_hi:[1,0]
	s_nop 0
	v_exp_f32_e32 v52, v52
	v_exp_f32_e32 v53, v53
	s_nop 0
	v_pk_mul_f32 v[48:49], v[52:53], v[48:49]
	s_nop 0
	v_pk_mul_f32 v[52:53], v[50:51], v[48:49]
	v_pk_fma_f32 v[48:49], v[50:51], v[48:49], v[50:51] neg_lo:[1,0,0] neg_hi:[1,0,0]
	v_cvt_pk_bf16_f32 v50, v56, v57
	s_nop 0
	v_cndmask_b32_e32 v52, v48, v52, vcc
	v_cmp_gt_f32_e32 vcc, 0, v51
	v_cvt_pk_bf16_f32 v48, v60, v61
	s_nop 1
	v_cndmask_b32_e32 v51, v49, v53, vcc
	v_cvt_pk_bf16_f32 v49, v58, v59
	v_cvt_pk_bf16_f32 v51, v52, v51
	flat_store_dwordx4 v[64:65], v[48:51] offset:256
	s_nop 0
	s_nop 0
	v_pk_mul_f32 v[44:45], v[44:45], v[176:177] op_sel_hi:[1,0]
	s_nop 0
	v_and_b32_e32 v53, 0x7fffffff, v45
	v_and_b32_e32 v52, 0x7fffffff, v44
	v_pk_fma_f32 v[52:53], v[52:53], s[36:37], 1.0 op_sel_hi:[1,0,0]
	v_pk_mul_f32 v[56:57], v[44:45], v[44:45]
	v_rcp_f32_e32 v52, v52
	v_rcp_f32_e32 v53, v53
	v_pk_mul_f32 v[56:57], v[56:57], s[58:59] op_sel_hi:[1,0]
	v_pk_mul_f32 v[46:47], v[46:47], v[176:177] op_sel_hi:[1,0]
	v_exp_f32_e32 v56, v56
	v_pk_fma_f32 v[54:55], v[52:53], s[12:13], v[120:121] op_sel_hi:[1,0,0]
	v_exp_f32_e32 v57, v57
	v_pk_fma_f32 v[54:55], v[52:53], v[54:55], s[8:9] op_sel_hi:[1,1,0]
	v_cmp_gt_f32_e32 vcc, 0, v44
	v_pk_fma_f32 v[54:55], v[52:53], v[54:55], s[24:25] op_sel_hi:[1,1,0]
	v_pk_mul_f32 v[42:43], v[42:43], v[176:177] op_sel_hi:[1,0]
	v_pk_fma_f32 v[54:55], v[52:53], v[54:55], s[56:57] op_sel_hi:[1,1,0]
	v_pk_mul_f32 v[40:41], v[40:41], v[176:177] op_sel_hi:[1,0]
	v_pk_mul_f32 v[52:53], v[52:53], v[54:55]
	v_pk_mul_f32 v[54:55], v[46:47], v[46:47]
	v_pk_mul_f32 v[52:53], v[56:57], v[52:53]
	v_lshl_add_u64 v[48:49], v[128:129], 0, s[10:11]
	v_pk_mul_f32 v[56:57], v[44:45], v[52:53]
	v_pk_fma_f32 v[52:53], v[44:45], v[52:53], v[44:45] neg_lo:[1,0,0] neg_hi:[1,0,0]
	v_and_b32_e32 v44, 0x7fffffff, v46
	v_cndmask_b32_e32 v51, v52, v56, vcc
	v_cmp_gt_f32_e32 vcc, 0, v45
	v_and_b32_e32 v45, 0x7fffffff, v47
	v_pk_fma_f32 v[44:45], v[44:45], s[36:37], 1.0 op_sel_hi:[1,0,0]
	v_cndmask_b32_e32 v56, v53, v57, vcc
	v_rcp_f32_e32 v44, v44
	v_rcp_f32_e32 v45, v45
	v_cmp_gt_f32_e32 vcc, 0, v46
	s_mov_b32 s10, 0x24000
	v_pk_mul_f32 v[36:37], v[36:37], v[176:177] op_sel_hi:[1,0]
	v_pk_fma_f32 v[52:53], v[44:45], s[12:13], v[120:121] op_sel_hi:[1,0,0]
	v_pk_mul_f32 v[38:39], v[38:39], v[176:177] op_sel_hi:[1,0]
	v_pk_fma_f32 v[52:53], v[44:45], v[52:53], s[8:9] op_sel_hi:[1,1,0]
	v_pk_mul_f32 v[32:33], v[32:33], v[176:177] op_sel_hi:[1,0]
	v_pk_fma_f32 v[52:53], v[44:45], v[52:53], s[24:25] op_sel_hi:[1,1,0]
	v_pk_mul_f32 v[34:35], v[34:35], v[176:177] op_sel_hi:[1,0]
	v_pk_fma_f32 v[52:53], v[44:45], v[52:53], s[56:57] op_sel_hi:[1,1,0]
	s_nop 0
	v_pk_mul_f32 v[44:45], v[44:45], v[52:53]
	v_pk_mul_f32 v[52:53], v[54:55], s[58:59] op_sel_hi:[1,0]
	s_nop 0
	v_exp_f32_e32 v52, v52
	v_exp_f32_e32 v53, v53
	s_nop 0
	v_pk_mul_f32 v[44:45], v[52:53], v[44:45]
	s_nop 0
	v_pk_mul_f32 v[52:53], v[46:47], v[44:45]
; __device__ __forceinline__ unsigned pkbf(float lo, float hi) { unsigned r; asm("v_cvt_pk_bf16_f32 %0, %1, %2" : "=v"(r) : "v"(lo), "v"(hi)); return r; }
; __device__ __forceinline__ f32x2 gelu_pk(f32x2 v) {
;     const f32x2 av = __builtin_elementwise_abs(v), d = av * 0.2316418882f + 1.0f;
;     f32x2 t; t.x = __builtin_amdgcn_rcpf(d.x); t.y = __builtin_amdgcn_rcpf(d.y);
;     f32x2 q = t * 0.5307027145f + (-0.7265760135f); q = q * t + 0.7107068705f; q = q * t + (-0.142248368f); q = q * t + 0.127414796f; q = q * t;
;     const f32x2 s = (v * v) * (-0.72134752044f);
;     f32x2 e; e.x = __builtin_amdgcn_exp2f(s.x); e.y = __builtin_amdgcn_exp2f(s.y);
;     const f32x2 m = v * (q * e), r = v - m;
;     f32x2 o; o.x = v.x < 0.f ? m.x : r.x; o.y = v.y < 0.f ? m.y : r.y; return o;
; }
;     __device__ __forceinline__ void operator()(const f32x4 (&acc)[2][2][4][2], const Unit& u, int wr, int wc, int fr, int fq) const {
;     ...
;                 for (int m = 0; m < 4; ++m) { const int row = row0 + ai * HALF + m * 16; const float rs = rinv[row]; bf16_t* rowp = base + (size_t)row * 512;
; #pragma unroll
;                     for (int bj = 0; bj < 2; ++bj) { f32x4 v0 = acc[ai][bj][m][0] * rs, v1 = acc[ai][bj][m][1] * rs;
;                         f32x2 a = gelu_pk((f32x2){v0[0], v0[1]}), b = gelu_pk((f32x2){v0[2], v0[3]}), c = gelu_pk((f32x2){v1[0], v1[1]}), d = gelu_pk((f32x2){v1[2], v1[3]});
;                         u32x4 w; w.x = pkbf(a.x, a.y); w.y = pkbf(b.x, b.y); w.z = pkbf(c.x, c.y); w.w = pkbf(d.x, d.y);
;                         *(u32x4*)(rowp + bj * HALF) = w; } }
	v_pk_fma_f32 v[44:45], v[46:47], v[44:45], v[46:47] neg_lo:[1,0,0] neg_hi:[1,0,0]
	s_nop 0
	v_cndmask_b32_e32 v54, v44, v52, vcc
	v_cmp_gt_f32_e32 vcc, 0, v47
	v_and_b32_e32 v44, 0x7fffffff, v40
	s_nop 0
	v_cndmask_b32_e32 v55, v45, v53, vcc
	v_and_b32_e32 v45, 0x7fffffff, v41
	v_pk_fma_f32 v[44:45], v[44:45], s[36:37], 1.0 op_sel_hi:[1,0,0]
	v_pk_mul_f32 v[52:53], v[40:41], v[40:41]
	v_rcp_f32_e32 v44, v44
	v_rcp_f32_e32 v45, v45
	v_pk_mul_f32 v[52:53], v[52:53], s[58:59] op_sel_hi:[1,0]
	v_cmp_gt_f32_e32 vcc, 0, v40
	v_exp_f32_e32 v52, v52
	v_pk_fma_f32 v[46:47], v[44:45], s[12:13], v[120:121] op_sel_hi:[1,0,0]
	v_exp_f32_e32 v53, v53
	v_pk_fma_f32 v[46:47], v[44:45], v[46:47], s[8:9] op_sel_hi:[1,1,0]
	s_nop 0
	v_pk_fma_f32 v[46:47], v[44:45], v[46:47], s[24:25] op_sel_hi:[1,1,0]
	s_nop 0
	v_pk_fma_f32 v[46:47], v[44:45], v[46:47], s[56:57] op_sel_hi:[1,1,0]
	s_nop 0
	v_pk_mul_f32 v[44:45], v[44:45], v[46:47]
	v_pk_mul_f32 v[46:47], v[42:43], v[42:43]
	v_pk_mul_f32 v[44:45], v[52:53], v[44:45]
	s_nop 0
	v_pk_mul_f32 v[52:53], v[40:41], v[44:45]
	v_pk_fma_f32 v[44:45], v[40:41], v[44:45], v[40:41] neg_lo:[1,0,0] neg_hi:[1,0,0]
	v_and_b32_e32 v40, 0x7fffffff, v42
	v_cndmask_b32_e32 v52, v44, v52, vcc
	v_cmp_gt_f32_e32 vcc, 0, v41
	v_and_b32_e32 v41, 0x7fffffff, v43
	v_pk_fma_f32 v[40:41], v[40:41], s[36:37], 1.0 op_sel_hi:[1,0,0]
	v_cndmask_b32_e32 v53, v45, v53, vcc
	v_rcp_f32_e32 v40, v40
	v_rcp_f32_e32 v41, v41
	v_cmp_gt_f32_e32 vcc, 0, v42
	v_pk_fma_f32 v[44:45], v[40:41], s[12:13], v[120:121] op_sel_hi:[1,0,0]
	s_nop 0
	v_pk_fma_f32 v[44:45], v[40:41], v[44:45], s[8:9] op_sel_hi:[1,1,0]
	s_nop 0
	v_pk_fma_f32 v[44:45], v[40:41], v[44:45], s[24:25] op_sel_hi:[1,1,0]
	s_nop 0
	v_pk_fma_f32 v[44:45], v[40:41], v[44:45], s[56:57] op_sel_hi:[1,1,0]
	s_nop 0
	v_pk_mul_f32 v[40:41], v[40:41], v[44:45]
	v_pk_mul_f32 v[44:45], v[46:47], s[58:59] op_sel_hi:[1,0]
	s_nop 0
	v_exp_f32_e32 v44, v44
	v_exp_f32_e32 v45, v45
	s_nop 0
	v_pk_mul_f32 v[40:41], v[44:45], v[40:41]
	s_nop 0
	v_pk_mul_f32 v[44:45], v[42:43], v[40:41]
	v_pk_fma_f32 v[40:41], v[42:43], v[40:41], v[42:43] neg_lo:[1,0,0] neg_hi:[1,0,0]
	v_cvt_pk_bf16_f32 v42, v52, v53
	s_nop 0
	v_cndmask_b32_e32 v44, v40, v44, vcc
	v_cmp_gt_f32_e32 vcc, 0, v43
	v_cvt_pk_bf16_f32 v40, v51, v56
	s_nop 1
	v_cndmask_b32_e32 v43, v41, v45, vcc
	v_cvt_pk_bf16_f32 v43, v44, v43
	v_add_co_u32_e32 v44, vcc, s10, v128
	v_cvt_pk_bf16_f32 v41, v54, v55
	s_mov_b32 s10, 0x28000
	s_nop 0
	v_addc_co_u32_e32 v45, vcc, 0, v129, vcc
	flat_store_dwordx4 v[44:45], v[40:43]
	v_pk_mul_f32 v[44:45], v[36:37], v[36:37]
	v_cmp_gt_f32_e32 vcc, 0, v36
	v_and_b32_e32 v41, 0x7fffffff, v37
	v_and_b32_e32 v40, 0x7fffffff, v36
	v_pk_fma_f32 v[40:41], v[40:41], s[36:37], 1.0 op_sel_hi:[1,0,0]
	v_pk_mul_f32 v[44:45], v[44:45], s[58:59] op_sel_hi:[1,0]
	v_rcp_f32_e32 v40, v40
	v_rcp_f32_e32 v41, v41
	v_exp_f32_e32 v44, v44
	v_exp_f32_e32 v45, v45
	v_pk_fma_f32 v[42:43], v[40:41], s[12:13], v[120:121] op_sel_hi:[1,0,0]
	s_nop 0
	v_pk_fma_f32 v[42:43], v[40:41], v[42:43], s[8:9] op_sel_hi:[1,1,0]
	s_nop 0
	v_pk_fma_f32 v[42:43], v[40:41], v[42:43], s[24:25] op_sel_hi:[1,1,0]
	s_nop 0
	v_pk_fma_f32 v[42:43], v[40:41], v[42:43], s[56:57] op_sel_hi:[1,1,0]
	s_nop 0
	v_pk_mul_f32 v[40:41], v[40:41], v[42:43]
	v_pk_mul_f32 v[42:43], v[38:39], v[38:39]
	v_pk_mul_f32 v[40:41], v[44:45], v[40:41]
	s_nop 0
	v_pk_mul_f32 v[44:45], v[36:37], v[40:41]
	v_pk_fma_f32 v[40:41], v[36:37], v[40:41], v[36:37] neg_lo:[1,0,0] neg_hi:[1,0,0]
	v_and_b32_e32 v36, 0x7fffffff, v38
	v_cndmask_b32_e32 v44, v40, v44, vcc
	v_cmp_gt_f32_e32 vcc, 0, v37
	v_and_b32_e32 v37, 0x7fffffff, v39
	v_pk_fma_f32 v[36:37], v[36:37], s[36:37], 1.0 op_sel_hi:[1,0,0]
	v_cndmask_b32_e32 v45, v41, v45, vcc
	v_rcp_f32_e32 v36, v36
	v_rcp_f32_e32 v37, v37
	v_cmp_gt_f32_e32 vcc, 0, v38
	v_pk_fma_f32 v[40:41], v[36:37], s[12:13], v[120:121] op_sel_hi:[1,0,0]
	s_nop 0
	v_pk_fma_f32 v[40:41], v[36:37], v[40:41], s[8:9] op_sel_hi:[1,1,0]
	s_nop 0
	v_pk_fma_f32 v[40:41], v[36:37], v[40:41], s[24:25] op_sel_hi:[1,1,0]
	s_nop 0
	v_pk_fma_f32 v[40:41], v[36:37], v[40:41], s[56:57] op_sel_hi:[1,1,0]
	s_nop 0
	v_pk_mul_f32 v[36:37], v[36:37], v[40:41]
	v_pk_mul_f32 v[40:41], v[42:43], s[58:59] op_sel_hi:[1,0]
	s_nop 0
	v_exp_f32_e32 v40, v40
	v_exp_f32_e32 v41, v41
	s_nop 0
	v_pk_mul_f32 v[36:37], v[40:41], v[36:37]
	s_nop 0
	v_pk_mul_f32 v[40:41], v[38:39], v[36:37]
	v_pk_fma_f32 v[36:37], v[38:39], v[36:37], v[38:39] neg_lo:[1,0,0] neg_hi:[1,0,0]
	s_nop 0
	v_cndmask_b32_e32 v42, v36, v40, vcc
	v_cmp_gt_f32_e32 vcc, 0, v39
	v_and_b32_e32 v36, 0x7fffffff, v32
	s_nop 0
	v_cndmask_b32_e32 v43, v37, v41, vcc
	v_and_b32_e32 v37, 0x7fffffff, v33
	v_pk_fma_f32 v[36:37], v[36:37], s[36:37], 1.0 op_sel_hi:[1,0,0]
	v_pk_mul_f32 v[40:41], v[32:33], v[32:33]
	v_rcp_f32_e32 v36, v36
	v_rcp_f32_e32 v37, v37
	v_pk_mul_f32 v[40:41], v[40:41], s[58:59] op_sel_hi:[1,0]
	v_cmp_gt_f32_e32 vcc, 0, v32
	v_exp_f32_e32 v40, v40
	v_pk_fma_f32 v[38:39], v[36:37], s[12:13], v[120:121] op_sel_hi:[1,0,0]
	v_exp_f32_e32 v41, v41
	v_pk_fma_f32 v[38:39], v[36:37], v[38:39], s[8:9] op_sel_hi:[1,1,0]
	s_nop 0
	v_pk_fma_f32 v[38:39], v[36:37], v[38:39], s[24:25] op_sel_hi:[1,1,0]
	s_nop 0
	v_pk_fma_f32 v[38:39], v[36:37], v[38:39], s[56:57] op_sel_hi:[1,1,0]
	s_nop 0
	v_pk_mul_f32 v[36:37], v[36:37], v[38:39]
	v_pk_mul_f32 v[38:39], v[34:35], v[34:35]
	v_pk_mul_f32 v[36:37], v[40:41], v[36:37]
	s_nop 0
	v_pk_mul_f32 v[40:41], v[32:33], v[36:37]
	v_pk_fma_f32 v[36:37], v[32:33], v[36:37], v[32:33] neg_lo:[1,0,0] neg_hi:[1,0,0]
	v_and_b32_e32 v32, 0x7fffffff, v34
	v_cndmask_b32_e32 v40, v36, v40, vcc
	v_cmp_gt_f32_e32 vcc, 0, v33
; __device__ __forceinline__ unsigned pkbf(float lo, float hi) { unsigned r; asm("v_cvt_pk_bf16_f32 %0, %1, %2" : "=v"(r) : "v"(lo), "v"(hi)); return r; }
; __device__ __forceinline__ f32x2 gelu_pk(f32x2 v) {
;     const f32x2 av = __builtin_elementwise_abs(v), d = av * 0.2316418882f + 1.0f;
;     f32x2 t; t.x = __builtin_amdgcn_rcpf(d.x); t.y = __builtin_amdgcn_rcpf(d.y);
;     f32x2 q = t * 0.5307027145f + (-0.7265760135f); q = q * t + 0.7107068705f; q = q * t + (-0.142248368f); q = q * t + 0.127414796f; q = q * t;
;     const f32x2 s = (v * v) * (-0.72134752044f);
;     f32x2 e; e.x = __builtin_amdgcn_exp2f(s.x); e.y = __builtin_amdgcn_exp2f(s.y);
;     const f32x2 m = v * (q * e), r = v - m;
;     f32x2 o; o.x = v.x < 0.f ? m.x : r.x; o.y = v.y < 0.f ? m.y : r.y; return o;
; }
;     __device__ __forceinline__ void operator()(const f32x4 (&acc)[2][2][4][2], const Unit& u, int wr, int wc, int fr, int fq) const {
;     ...
;                 for (int m = 0; m < 4; ++m) { const int row = row0 + ai * HALF + m * 16; const float rs = rinv[row]; bf16_t* rowp = base + (size_t)row * 512;
; #pragma unroll
;                     for (int bj = 0; bj < 2; ++bj) { f32x4 v0 = acc[ai][bj][m][0] * rs, v1 = acc[ai][bj][m][1] * rs;
;                         f32x2 a = gelu_pk((f32x2){v0[0], v0[1]}), b = gelu_pk((f32x2){v0[2], v0[3]}), c = gelu_pk((f32x2){v1[0], v1[1]}), d = gelu_pk((f32x2){v1[2], v1[3]});
;                         u32x4 w; w.x = pkbf(a.x, a.y); w.y = pkbf(b.x, b.y); w.z = pkbf(c.x, c.y); w.w = pkbf(d.x, d.y);
;                         *(u32x4*)(rowp + bj * HALF) = w; } }
	v_and_b32_e32 v33, 0x7fffffff, v35
	v_pk_fma_f32 v[32:33], v[32:33], s[36:37], 1.0 op_sel_hi:[1,0,0]
	v_cndmask_b32_e32 v41, v37, v41, vcc
	v_rcp_f32_e32 v32, v32
	v_rcp_f32_e32 v33, v33
	v_cmp_gt_f32_e32 vcc, 0, v34
	v_pk_fma_f32 v[36:37], v[32:33], s[12:13], v[120:121] op_sel_hi:[1,0,0]
	s_nop 0
	v_pk_fma_f32 v[36:37], v[32:33], v[36:37], s[8:9] op_sel_hi:[1,1,0]
	s_nop 0
	v_pk_fma_f32 v[36:37], v[32:33], v[36:37], s[24:25] op_sel_hi:[1,1,0]
	s_nop 0
	v_pk_fma_f32 v[36:37], v[32:33], v[36:37], s[56:57] op_sel_hi:[1,1,0]
	s_nop 0
	v_pk_mul_f32 v[32:33], v[32:33], v[36:37]
	v_pk_mul_f32 v[36:37], v[38:39], s[58:59] op_sel_hi:[1,0]
	s_nop 0
	v_exp_f32_e32 v36, v36
	v_exp_f32_e32 v37, v37
	s_nop 0
	v_pk_mul_f32 v[32:33], v[36:37], v[32:33]
	s_nop 0
	v_pk_mul_f32 v[36:37], v[34:35], v[32:33]
	v_pk_fma_f32 v[32:33], v[34:35], v[32:33], v[34:35] neg_lo:[1,0,0] neg_hi:[1,0,0]
	v_cvt_pk_bf16_f32 v34, v40, v41
	s_nop 0
	v_cndmask_b32_e32 v36, v32, v36, vcc
	v_cmp_gt_f32_e32 vcc, 0, v35
	v_cvt_pk_bf16_f32 v32, v44, v45
	s_nop 1
	v_cndmask_b32_e32 v35, v33, v37, vcc
	v_cvt_pk_bf16_f32 v33, v42, v43
	v_cvt_pk_bf16_f32 v35, v36, v35
	flat_store_dwordx4 v[48:49], v[32:35] offset:256
	s_nop 0
	s_nop 0
	v_pk_mul_f32 v[28:29], v[28:29], v[178:179] op_sel_hi:[1,0]
	s_nop 0
	v_and_b32_e32 v37, 0x7fffffff, v29
	v_and_b32_e32 v36, 0x7fffffff, v28
	v_pk_fma_f32 v[36:37], v[36:37], s[36:37], 1.0 op_sel_hi:[1,0,0]
	v_pk_mul_f32 v[40:41], v[28:29], v[28:29]
	v_rcp_f32_e32 v36, v36
	v_rcp_f32_e32 v37, v37
	v_pk_mul_f32 v[40:41], v[40:41], s[58:59] op_sel_hi:[1,0]
	v_pk_mul_f32 v[30:31], v[30:31], v[178:179] op_sel_hi:[1,0]
	v_exp_f32_e32 v40, v40
	v_pk_fma_f32 v[38:39], v[36:37], s[12:13], v[120:121] op_sel_hi:[1,0,0]
	v_exp_f32_e32 v41, v41
	v_pk_fma_f32 v[38:39], v[36:37], v[38:39], s[8:9] op_sel_hi:[1,1,0]
	v_cmp_gt_f32_e32 vcc, 0, v28
	v_pk_fma_f32 v[38:39], v[36:37], v[38:39], s[24:25] op_sel_hi:[1,1,0]
	v_pk_mul_f32 v[26:27], v[26:27], v[178:179] op_sel_hi:[1,0]
	v_pk_fma_f32 v[38:39], v[36:37], v[38:39], s[56:57] op_sel_hi:[1,1,0]
	v_pk_mul_f32 v[24:25], v[24:25], v[178:179] op_sel_hi:[1,0]
	v_pk_mul_f32 v[36:37], v[36:37], v[38:39]
	v_pk_mul_f32 v[38:39], v[30:31], v[30:31]
	v_pk_mul_f32 v[36:37], v[40:41], v[36:37]
	v_lshl_add_u64 v[32:33], v[128:129], 0, s[82:83]
	v_pk_mul_f32 v[40:41], v[28:29], v[36:37]
	v_pk_fma_f32 v[36:37], v[28:29], v[36:37], v[28:29] neg_lo:[1,0,0] neg_hi:[1,0,0]
	v_and_b32_e32 v28, 0x7fffffff, v30
	v_cndmask_b32_e32 v35, v36, v40, vcc
	v_cmp_gt_f32_e32 vcc, 0, v29
	v_and_b32_e32 v29, 0x7fffffff, v31
	v_pk_fma_f32 v[28:29], v[28:29], s[36:37], 1.0 op_sel_hi:[1,0,0]
	v_cndmask_b32_e32 v40, v37, v41, vcc
	v_rcp_f32_e32 v28, v28
	v_rcp_f32_e32 v29, v29
	v_cmp_gt_f32_e32 vcc, 0, v30
	v_pk_mul_f32 v[20:21], v[20:21], v[178:179] op_sel_hi:[1,0]
	v_pk_mul_f32 v[22:23], v[22:23], v[178:179] op_sel_hi:[1,0]
	v_pk_fma_f32 v[36:37], v[28:29], s[12:13], v[120:121] op_sel_hi:[1,0,0]
	v_pk_mul_f32 v[16:17], v[16:17], v[178:179] op_sel_hi:[1,0]
	v_pk_fma_f32 v[36:37], v[28:29], v[36:37], s[8:9] op_sel_hi:[1,1,0]
	v_pk_mul_f32 v[18:19], v[18:19], v[178:179] op_sel_hi:[1,0]
	v_pk_fma_f32 v[36:37], v[28:29], v[36:37], s[24:25] op_sel_hi:[1,1,0]
	s_mov_b64 s[82:83], 0x2c000
	v_pk_fma_f32 v[36:37], v[28:29], v[36:37], s[56:57] op_sel_hi:[1,1,0]
	s_nop 0
	v_pk_mul_f32 v[28:29], v[28:29], v[36:37]
	v_pk_mul_f32 v[36:37], v[38:39], s[58:59] op_sel_hi:[1,0]
	s_nop 0
	v_exp_f32_e32 v36, v36
	v_exp_f32_e32 v37, v37
	s_nop 0
	v_pk_mul_f32 v[28:29], v[36:37], v[28:29]
	s_nop 0
	v_pk_mul_f32 v[36:37], v[30:31], v[28:29]
	v_pk_fma_f32 v[28:29], v[30:31], v[28:29], v[30:31] neg_lo:[1,0,0] neg_hi:[1,0,0]
	s_nop 0
	v_cndmask_b32_e32 v38, v28, v36, vcc
	v_cmp_gt_f32_e32 vcc, 0, v31
	v_and_b32_e32 v28, 0x7fffffff, v24
	s_nop 0
	v_cndmask_b32_e32 v39, v29, v37, vcc
	v_and_b32_e32 v29, 0x7fffffff, v25
	v_pk_fma_f32 v[28:29], v[28:29], s[36:37], 1.0 op_sel_hi:[1,0,0]
	v_pk_mul_f32 v[36:37], v[24:25], v[24:25]
	v_rcp_f32_e32 v28, v28
	v_rcp_f32_e32 v29, v29
	v_pk_mul_f32 v[36:37], v[36:37], s[58:59] op_sel_hi:[1,0]
	v_cmp_gt_f32_e32 vcc, 0, v24
	v_exp_f32_e32 v36, v36
	v_pk_fma_f32 v[30:31], v[28:29], s[12:13], v[120:121] op_sel_hi:[1,0,0]
	v_exp_f32_e32 v37, v37
	v_pk_fma_f32 v[30:31], v[28:29], v[30:31], s[8:9] op_sel_hi:[1,1,0]
	s_nop 0
	v_pk_fma_f32 v[30:31], v[28:29], v[30:31], s[24:25] op_sel_hi:[1,1,0]
	s_nop 0
	v_pk_fma_f32 v[30:31], v[28:29], v[30:31], s[56:57] op_sel_hi:[1,1,0]
	s_nop 0
	v_pk_mul_f32 v[28:29], v[28:29], v[30:31]
	v_pk_mul_f32 v[30:31], v[26:27], v[26:27]
	v_pk_mul_f32 v[28:29], v[36:37], v[28:29]
	s_nop 0
	v_pk_mul_f32 v[36:37], v[24:25], v[28:29]
	v_pk_fma_f32 v[28:29], v[24:25], v[28:29], v[24:25] neg_lo:[1,0,0] neg_hi:[1,0,0]
	v_and_b32_e32 v24, 0x7fffffff, v26
	v_cndmask_b32_e32 v36, v28, v36, vcc
	v_cmp_gt_f32_e32 vcc, 0, v25
	v_and_b32_e32 v25, 0x7fffffff, v27
	v_pk_fma_f32 v[24:25], v[24:25], s[36:37], 1.0 op_sel_hi:[1,0,0]
	v_cndmask_b32_e32 v37, v29, v37, vcc
	v_rcp_f32_e32 v24, v24
	v_rcp_f32_e32 v25, v25
	v_cmp_gt_f32_e32 vcc, 0, v26
	v_pk_fma_f32 v[28:29], v[24:25], s[12:13], v[120:121] op_sel_hi:[1,0,0]
	s_nop 0
	v_pk_fma_f32 v[28:29], v[24:25], v[28:29], s[8:9] op_sel_hi:[1,1,0]
	s_nop 0
	v_pk_fma_f32 v[28:29], v[24:25], v[28:29], s[24:25] op_sel_hi:[1,1,0]
	s_nop 0
	v_pk_fma_f32 v[28:29], v[24:25], v[28:29], s[56:57] op_sel_hi:[1,1,0]
	s_nop 0
	v_pk_mul_f32 v[24:25], v[24:25], v[28:29]
	v_pk_mul_f32 v[28:29], v[30:31], s[58:59] op_sel_hi:[1,0]
	s_nop 0
	v_exp_f32_e32 v28, v28
	v_exp_f32_e32 v29, v29
	s_nop 0
	v_pk_mul_f32 v[24:25], v[28:29], v[24:25]
	s_nop 0
	v_pk_mul_f32 v[28:29], v[26:27], v[24:25]
; __device__ __forceinline__ unsigned pkbf(float lo, float hi) { unsigned r; asm("v_cvt_pk_bf16_f32 %0, %1, %2" : "=v"(r) : "v"(lo), "v"(hi)); return r; }
; __device__ __forceinline__ f32x2 gelu_pk(f32x2 v) {
;     const f32x2 av = __builtin_elementwise_abs(v), d = av * 0.2316418882f + 1.0f;
;     f32x2 t; t.x = __builtin_amdgcn_rcpf(d.x); t.y = __builtin_amdgcn_rcpf(d.y);
;     f32x2 q = t * 0.5307027145f + (-0.7265760135f); q = q * t + 0.7107068705f; q = q * t + (-0.142248368f); q = q * t + 0.127414796f; q = q * t;
;     const f32x2 s = (v * v) * (-0.72134752044f);
;     f32x2 e; e.x = __builtin_amdgcn_exp2f(s.x); e.y = __builtin_amdgcn_exp2f(s.y);
;     const f32x2 m = v * (q * e), r = v - m;
;     f32x2 o; o.x = v.x < 0.f ? m.x : r.x; o.y = v.y < 0.f ? m.y : r.y; return o;
; }
;     __device__ __forceinline__ void operator()(const f32x4 (&acc)[2][2][4][2], const Unit& u, int wr, int wc, int fr, int fq) const {
;     ...
;                 for (int m = 0; m < 4; ++m) { const int row = row0 + ai * HALF + m * 16; const float rs = rinv[row]; bf16_t* rowp = base + (size_t)row * 512;
; #pragma unroll
;                     for (int bj = 0; bj < 2; ++bj) { f32x4 v0 = acc[ai][bj][m][0] * rs, v1 = acc[ai][bj][m][1] * rs;
;                         f32x2 a = gelu_pk((f32x2){v0[0], v0[1]}), b = gelu_pk((f32x2){v0[2], v0[3]}), c = gelu_pk((f32x2){v1[0], v1[1]}), d = gelu_pk((f32x2){v1[2], v1[3]});
;                         u32x4 w; w.x = pkbf(a.x, a.y); w.y = pkbf(b.x, b.y); w.z = pkbf(c.x, c.y); w.w = pkbf(d.x, d.y);
;                         *(u32x4*)(rowp + bj * HALF) = w; } }
	v_pk_fma_f32 v[24:25], v[26:27], v[24:25], v[26:27] neg_lo:[1,0,0] neg_hi:[1,0,0]
	v_cvt_pk_bf16_f32 v26, v36, v37
	s_nop 0
	v_cndmask_b32_e32 v28, v24, v28, vcc
	v_cmp_gt_f32_e32 vcc, 0, v27
	v_cvt_pk_bf16_f32 v24, v35, v40
	s_nop 1
	v_cndmask_b32_e32 v27, v25, v29, vcc
	v_cvt_pk_bf16_f32 v27, v28, v27
	v_add_co_u32_e32 v28, vcc, s10, v128
	v_cvt_pk_bf16_f32 v25, v38, v39
	s_mov_b32 s10, 0x2c000
	s_nop 0
	v_addc_co_u32_e32 v29, vcc, 0, v129, vcc
	flat_store_dwordx4 v[28:29], v[24:27]
	v_pk_mul_f32 v[28:29], v[20:21], v[20:21]
	v_cmp_gt_f32_e32 vcc, 0, v20
	v_and_b32_e32 v25, 0x7fffffff, v21
	v_and_b32_e32 v24, 0x7fffffff, v20
	v_pk_fma_f32 v[24:25], v[24:25], s[36:37], 1.0 op_sel_hi:[1,0,0]
	v_pk_mul_f32 v[28:29], v[28:29], s[58:59] op_sel_hi:[1,0]
	v_rcp_f32_e32 v24, v24
	v_rcp_f32_e32 v25, v25
	v_exp_f32_e32 v28, v28
	v_exp_f32_e32 v29, v29
	v_pk_fma_f32 v[26:27], v[24:25], s[12:13], v[120:121] op_sel_hi:[1,0,0]
	s_nop 0
	v_pk_fma_f32 v[26:27], v[24:25], v[26:27], s[8:9] op_sel_hi:[1,1,0]
	s_nop 0
	v_pk_fma_f32 v[26:27], v[24:25], v[26:27], s[24:25] op_sel_hi:[1,1,0]
	s_nop 0
	v_pk_fma_f32 v[26:27], v[24:25], v[26:27], s[56:57] op_sel_hi:[1,1,0]
	s_nop 0
	v_pk_mul_f32 v[24:25], v[24:25], v[26:27]
	v_pk_mul_f32 v[26:27], v[22:23], v[22:23]
	v_pk_mul_f32 v[24:25], v[28:29], v[24:25]
	s_nop 0
	v_pk_mul_f32 v[28:29], v[20:21], v[24:25]
	v_pk_fma_f32 v[24:25], v[20:21], v[24:25], v[20:21] neg_lo:[1,0,0] neg_hi:[1,0,0]
	v_and_b32_e32 v20, 0x7fffffff, v22
	v_cndmask_b32_e32 v28, v24, v28, vcc
	v_cmp_gt_f32_e32 vcc, 0, v21
	v_and_b32_e32 v21, 0x7fffffff, v23
	v_pk_fma_f32 v[20:21], v[20:21], s[36:37], 1.0 op_sel_hi:[1,0,0]
	v_cndmask_b32_e32 v29, v25, v29, vcc
	v_rcp_f32_e32 v20, v20
	v_rcp_f32_e32 v21, v21
	v_cmp_gt_f32_e32 vcc, 0, v22
	v_pk_fma_f32 v[24:25], v[20:21], s[12:13], v[120:121] op_sel_hi:[1,0,0]
	s_nop 0
	v_pk_fma_f32 v[24:25], v[20:21], v[24:25], s[8:9] op_sel_hi:[1,1,0]
	s_nop 0
	v_pk_fma_f32 v[24:25], v[20:21], v[24:25], s[24:25] op_sel_hi:[1,1,0]
	s_nop 0
	v_pk_fma_f32 v[24:25], v[20:21], v[24:25], s[56:57] op_sel_hi:[1,1,0]
	s_nop 0
	v_pk_mul_f32 v[20:21], v[20:21], v[24:25]
	v_pk_mul_f32 v[24:25], v[26:27], s[58:59] op_sel_hi:[1,0]
	s_nop 0
	v_exp_f32_e32 v24, v24
	v_exp_f32_e32 v25, v25
	s_nop 0
	v_pk_mul_f32 v[20:21], v[24:25], v[20:21]
	s_nop 0
	v_pk_mul_f32 v[24:25], v[22:23], v[20:21]
	v_pk_fma_f32 v[20:21], v[22:23], v[20:21], v[22:23] neg_lo:[1,0,0] neg_hi:[1,0,0]
	s_nop 0
	v_cndmask_b32_e32 v26, v20, v24, vcc
	v_cmp_gt_f32_e32 vcc, 0, v23
	v_and_b32_e32 v20, 0x7fffffff, v16
	s_nop 0
	v_cndmask_b32_e32 v27, v21, v25, vcc
	v_and_b32_e32 v21, 0x7fffffff, v17
	v_pk_fma_f32 v[20:21], v[20:21], s[36:37], 1.0 op_sel_hi:[1,0,0]
	v_pk_mul_f32 v[24:25], v[16:17], v[16:17]
	v_rcp_f32_e32 v20, v20
	v_rcp_f32_e32 v21, v21
	v_pk_mul_f32 v[24:25], v[24:25], s[58:59] op_sel_hi:[1,0]
	v_cmp_gt_f32_e32 vcc, 0, v16
	v_exp_f32_e32 v24, v24
	v_pk_fma_f32 v[22:23], v[20:21], s[12:13], v[120:121] op_sel_hi:[1,0,0]
	v_exp_f32_e32 v25, v25
	v_pk_fma_f32 v[22:23], v[20:21], v[22:23], s[8:9] op_sel_hi:[1,1,0]
	s_nop 0
	v_pk_fma_f32 v[22:23], v[20:21], v[22:23], s[24:25] op_sel_hi:[1,1,0]
	s_nop 0
	v_pk_fma_f32 v[22:23], v[20:21], v[22:23], s[56:57] op_sel_hi:[1,1,0]
	s_nop 0
	v_pk_mul_f32 v[20:21], v[20:21], v[22:23]
	v_pk_mul_f32 v[22:23], v[18:19], v[18:19]
	v_pk_mul_f32 v[20:21], v[24:25], v[20:21]
	s_nop 0
	v_pk_mul_f32 v[24:25], v[16:17], v[20:21]
	v_pk_fma_f32 v[20:21], v[16:17], v[20:21], v[16:17] neg_lo:[1,0,0] neg_hi:[1,0,0]
	v_and_b32_e32 v16, 0x7fffffff, v18
	v_cndmask_b32_e32 v24, v20, v24, vcc
	v_cmp_gt_f32_e32 vcc, 0, v17
	v_and_b32_e32 v17, 0x7fffffff, v19
	v_pk_fma_f32 v[16:17], v[16:17], s[36:37], 1.0 op_sel_hi:[1,0,0]
	v_cndmask_b32_e32 v25, v21, v25, vcc
	v_rcp_f32_e32 v16, v16
	v_rcp_f32_e32 v17, v17
	v_cmp_gt_f32_e32 vcc, 0, v18
	v_pk_fma_f32 v[20:21], v[16:17], s[12:13], v[120:121] op_sel_hi:[1,0,0]
	s_nop 0
	v_pk_fma_f32 v[20:21], v[16:17], v[20:21], s[8:9] op_sel_hi:[1,1,0]
	s_nop 0
	v_pk_fma_f32 v[20:21], v[16:17], v[20:21], s[24:25] op_sel_hi:[1,1,0]
	s_nop 0
	v_pk_fma_f32 v[20:21], v[16:17], v[20:21], s[56:57] op_sel_hi:[1,1,0]
	s_nop 0
	v_pk_mul_f32 v[16:17], v[16:17], v[20:21]
	v_pk_mul_f32 v[20:21], v[22:23], s[58:59] op_sel_hi:[1,0]
	s_nop 0
	v_exp_f32_e32 v20, v20
	v_exp_f32_e32 v21, v21
	s_nop 0
	v_pk_mul_f32 v[16:17], v[20:21], v[16:17]
	s_nop 0
	v_pk_mul_f32 v[20:21], v[18:19], v[16:17]
	v_pk_fma_f32 v[16:17], v[18:19], v[16:17], v[18:19] neg_lo:[1,0,0] neg_hi:[1,0,0]
	v_cvt_pk_bf16_f32 v18, v24, v25
	s_nop 0
	v_cndmask_b32_e32 v20, v16, v20, vcc
	v_cmp_gt_f32_e32 vcc, 0, v19
	v_cvt_pk_bf16_f32 v16, v28, v29
	s_nop 1
	v_cndmask_b32_e32 v19, v17, v21, vcc
	v_cvt_pk_bf16_f32 v17, v26, v27
	v_cvt_pk_bf16_f32 v19, v20, v19
	flat_store_dwordx4 v[32:33], v[16:19] offset:256
	s_nop 0
	s_nop 0
	v_pk_mul_f32 v[12:13], v[12:13], v[180:181] op_sel_hi:[1,0]
	s_nop 0
	v_and_b32_e32 v21, 0x7fffffff, v13
	v_and_b32_e32 v20, 0x7fffffff, v12
	v_pk_fma_f32 v[20:21], v[20:21], s[36:37], 1.0 op_sel_hi:[1,0,0]
	v_pk_mul_f32 v[24:25], v[12:13], v[12:13]
	v_rcp_f32_e32 v20, v20
	v_rcp_f32_e32 v21, v21
	v_pk_mul_f32 v[24:25], v[24:25], s[58:59] op_sel_hi:[1,0]
	v_pk_mul_f32 v[14:15], v[14:15], v[180:181] op_sel_hi:[1,0]
	v_exp_f32_e32 v24, v24
	v_pk_fma_f32 v[22:23], v[20:21], s[12:13], v[120:121] op_sel_hi:[1,0,0]
	v_exp_f32_e32 v25, v25
	v_pk_fma_f32 v[22:23], v[20:21], v[22:23], s[8:9] op_sel_hi:[1,1,0]
	v_cmp_gt_f32_e32 vcc, 0, v12
	v_pk_fma_f32 v[22:23], v[20:21], v[22:23], s[24:25] op_sel_hi:[1,1,0]
	v_pk_mul_f32 v[10:11], v[10:11], v[180:181] op_sel_hi:[1,0]
	v_pk_fma_f32 v[22:23], v[20:21], v[22:23], s[56:57] op_sel_hi:[1,1,0]
; __device__ __forceinline__ unsigned pkbf(float lo, float hi) { unsigned r; asm("v_cvt_pk_bf16_f32 %0, %1, %2" : "=v"(r) : "v"(lo), "v"(hi)); return r; }
; __device__ __forceinline__ f32x2 gelu_pk(f32x2 v) {
;     const f32x2 av = __builtin_elementwise_abs(v), d = av * 0.2316418882f + 1.0f;
;     f32x2 t; t.x = __builtin_amdgcn_rcpf(d.x); t.y = __builtin_amdgcn_rcpf(d.y);
;     f32x2 q = t * 0.5307027145f + (-0.7265760135f); q = q * t + 0.7107068705f; q = q * t + (-0.142248368f); q = q * t + 0.127414796f; q = q * t;
;     const f32x2 s = (v * v) * (-0.72134752044f);
;     f32x2 e; e.x = __builtin_amdgcn_exp2f(s.x); e.y = __builtin_amdgcn_exp2f(s.y);
;     const f32x2 m = v * (q * e), r = v - m;
;     f32x2 o; o.x = v.x < 0.f ? m.x : r.x; o.y = v.y < 0.f ? m.y : r.y; return o;
; }
;     __device__ __forceinline__ void operator()(const f32x4 (&acc)[2][2][4][2], const Unit& u, int wr, int wc, int fr, int fq) const {
;     ...
;                 for (int m = 0; m < 4; ++m) { const int row = row0 + ai * HALF + m * 16; const float rs = rinv[row]; bf16_t* rowp = base + (size_t)row * 512;
; #pragma unroll
;                     for (int bj = 0; bj < 2; ++bj) { f32x4 v0 = acc[ai][bj][m][0] * rs, v1 = acc[ai][bj][m][1] * rs;
;                         f32x2 a = gelu_pk((f32x2){v0[0], v0[1]}), b = gelu_pk((f32x2){v0[2], v0[3]}), c = gelu_pk((f32x2){v1[0], v1[1]}), d = gelu_pk((f32x2){v1[2], v1[3]});
;                         u32x4 w; w.x = pkbf(a.x, a.y); w.y = pkbf(b.x, b.y); w.z = pkbf(c.x, c.y); w.w = pkbf(d.x, d.y);
;                         *(u32x4*)(rowp + bj * HALF) = w; } }
	v_pk_mul_f32 v[8:9], v[8:9], v[180:181] op_sel_hi:[1,0]
	v_pk_mul_f32 v[20:21], v[20:21], v[22:23]
	v_pk_mul_f32 v[22:23], v[14:15], v[14:15]
	v_pk_mul_f32 v[20:21], v[24:25], v[20:21]
	v_lshl_add_u64 v[16:17], v[128:129], 0, s[82:83]
	v_pk_mul_f32 v[24:25], v[12:13], v[20:21]
	v_pk_fma_f32 v[20:21], v[12:13], v[20:21], v[12:13] neg_lo:[1,0,0] neg_hi:[1,0,0]
	v_and_b32_e32 v12, 0x7fffffff, v14
	v_cndmask_b32_e32 v19, v20, v24, vcc
	v_cmp_gt_f32_e32 vcc, 0, v13
	v_and_b32_e32 v13, 0x7fffffff, v15
	v_pk_fma_f32 v[12:13], v[12:13], s[36:37], 1.0 op_sel_hi:[1,0,0]
	v_cndmask_b32_e32 v24, v21, v25, vcc
	v_rcp_f32_e32 v12, v12
	v_rcp_f32_e32 v13, v13
	v_cmp_gt_f32_e32 vcc, 0, v14
	v_pk_mul_f32 v[4:5], v[4:5], v[180:181] op_sel_hi:[1,0]
	v_pk_mul_f32 v[6:7], v[6:7], v[180:181] op_sel_hi:[1,0]
	v_pk_fma_f32 v[20:21], v[12:13], s[12:13], v[120:121] op_sel_hi:[1,0,0]
	v_pk_mul_f32 v[0:1], v[0:1], v[180:181] op_sel_hi:[1,0]
	v_pk_fma_f32 v[20:21], v[12:13], v[20:21], s[8:9] op_sel_hi:[1,1,0]
	v_pk_mul_f32 v[2:3], v[2:3], v[180:181] op_sel_hi:[1,0]
	v_pk_fma_f32 v[20:21], v[12:13], v[20:21], s[24:25] op_sel_hi:[1,1,0]
	s_nop 0
	v_pk_fma_f32 v[20:21], v[12:13], v[20:21], s[56:57] op_sel_hi:[1,1,0]
	s_nop 0
	v_pk_mul_f32 v[12:13], v[12:13], v[20:21]
	v_pk_mul_f32 v[20:21], v[22:23], s[58:59] op_sel_hi:[1,0]
	s_nop 0
	v_exp_f32_e32 v20, v20
	v_exp_f32_e32 v21, v21
	s_nop 0
	v_pk_mul_f32 v[12:13], v[20:21], v[12:13]
	s_nop 0
	v_pk_mul_f32 v[20:21], v[14:15], v[12:13]
	v_pk_fma_f32 v[12:13], v[14:15], v[12:13], v[14:15] neg_lo:[1,0,0] neg_hi:[1,0,0]
	s_nop 0
	v_cndmask_b32_e32 v22, v12, v20, vcc
	v_cmp_gt_f32_e32 vcc, 0, v15
	v_and_b32_e32 v12, 0x7fffffff, v8
	s_nop 0
	v_cndmask_b32_e32 v23, v13, v21, vcc
	v_and_b32_e32 v13, 0x7fffffff, v9
	v_pk_fma_f32 v[12:13], v[12:13], s[36:37], 1.0 op_sel_hi:[1,0,0]
	v_pk_mul_f32 v[20:21], v[8:9], v[8:9]
	v_rcp_f32_e32 v12, v12
	v_rcp_f32_e32 v13, v13
	v_pk_mul_f32 v[20:21], v[20:21], s[58:59] op_sel_hi:[1,0]
	v_cmp_gt_f32_e32 vcc, 0, v8
	v_exp_f32_e32 v20, v20
	v_pk_fma_f32 v[14:15], v[12:13], s[12:13], v[120:121] op_sel_hi:[1,0,0]
	v_exp_f32_e32 v21, v21
	v_pk_fma_f32 v[14:15], v[12:13], v[14:15], s[8:9] op_sel_hi:[1,1,0]
	s_nop 0
	v_pk_fma_f32 v[14:15], v[12:13], v[14:15], s[24:25] op_sel_hi:[1,1,0]
	s_nop 0
	v_pk_fma_f32 v[14:15], v[12:13], v[14:15], s[56:57] op_sel_hi:[1,1,0]
	s_nop 0
	v_pk_mul_f32 v[12:13], v[12:13], v[14:15]
	v_pk_mul_f32 v[14:15], v[10:11], v[10:11]
	v_pk_mul_f32 v[12:13], v[20:21], v[12:13]
	s_nop 0
	v_pk_mul_f32 v[20:21], v[8:9], v[12:13]
	v_pk_fma_f32 v[12:13], v[8:9], v[12:13], v[8:9] neg_lo:[1,0,0] neg_hi:[1,0,0]
	v_and_b32_e32 v8, 0x7fffffff, v10
	v_cndmask_b32_e32 v20, v12, v20, vcc
	v_cmp_gt_f32_e32 vcc, 0, v9
	v_and_b32_e32 v9, 0x7fffffff, v11
	v_pk_fma_f32 v[8:9], v[8:9], s[36:37], 1.0 op_sel_hi:[1,0,0]
	v_cndmask_b32_e32 v21, v13, v21, vcc
	v_rcp_f32_e32 v8, v8
	v_rcp_f32_e32 v9, v9
	v_cmp_gt_f32_e32 vcc, 0, v10
	v_pk_fma_f32 v[12:13], v[8:9], s[12:13], v[120:121] op_sel_hi:[1,0,0]
	s_nop 0
	v_pk_fma_f32 v[12:13], v[8:9], v[12:13], s[8:9] op_sel_hi:[1,1,0]
	s_nop 0
	v_pk_fma_f32 v[12:13], v[8:9], v[12:13], s[24:25] op_sel_hi:[1,1,0]
	s_nop 0
	v_pk_fma_f32 v[12:13], v[8:9], v[12:13], s[56:57] op_sel_hi:[1,1,0]
	s_nop 0
	v_pk_mul_f32 v[8:9], v[8:9], v[12:13]
	v_pk_mul_f32 v[12:13], v[14:15], s[58:59] op_sel_hi:[1,0]
	s_nop 0
	v_exp_f32_e32 v12, v12
	v_exp_f32_e32 v13, v13
	s_nop 0
	v_pk_mul_f32 v[8:9], v[12:13], v[8:9]
	s_nop 0
	v_pk_mul_f32 v[12:13], v[10:11], v[8:9]
	v_pk_fma_f32 v[8:9], v[10:11], v[8:9], v[10:11] neg_lo:[1,0,0] neg_hi:[1,0,0]
	v_cvt_pk_bf16_f32 v10, v20, v21
	s_nop 0
	v_cndmask_b32_e32 v12, v8, v12, vcc
	v_cmp_gt_f32_e32 vcc, 0, v11
	v_cvt_pk_bf16_f32 v8, v19, v24
	s_nop 1
	v_cndmask_b32_e32 v11, v9, v13, vcc
	v_cvt_pk_bf16_f32 v11, v12, v11
	v_add_co_u32_e32 v12, vcc, s10, v128
	v_cvt_pk_bf16_f32 v9, v22, v23
	s_nop 1
	v_addc_co_u32_e32 v13, vcc, 0, v129, vcc
	flat_store_dwordx4 v[12:13], v[8:11]
	v_pk_mul_f32 v[12:13], v[4:5], v[4:5]
	v_cmp_gt_f32_e32 vcc, 0, v4
; __device__ __forceinline__ unsigned pkbf(float lo, float hi) { unsigned r; asm("v_cvt_pk_bf16_f32 %0, %1, %2" : "=v"(r) : "v"(lo), "v"(hi)); return r; }
; __device__ __forceinline__ f32x2 gelu_pk(f32x2 v) {
;     const f32x2 av = __builtin_elementwise_abs(v), d = av * 0.2316418882f + 1.0f;
;     f32x2 t; t.x = __builtin_amdgcn_rcpf(d.x); t.y = __builtin_amdgcn_rcpf(d.y);
;     f32x2 q = t * 0.5307027145f + (-0.7265760135f); q = q * t + 0.7107068705f; q = q * t + (-0.142248368f); q = q * t + 0.127414796f; q = q * t;
;     const f32x2 s = (v * v) * (-0.72134752044f);
;     f32x2 e; e.x = __builtin_amdgcn_exp2f(s.x); e.y = __builtin_amdgcn_exp2f(s.y);
;     const f32x2 m = v * (q * e), r = v - m;
;     f32x2 o; o.x = v.x < 0.f ? m.x : r.x; o.y = v.y < 0.f ? m.y : r.y; return o;
; }
;     __device__ __forceinline__ void operator()(const f32x4 (&acc)[2][2][4][2], const Unit& u, int wr, int wc, int fr, int fq) const {
;     ...
;                 for (int m = 0; m < 4; ++m) { const int row = row0 + ai * HALF + m * 16; const float rs = rinv[row]; bf16_t* rowp = base + (size_t)row * 512;
; #pragma unroll
;                     for (int bj = 0; bj < 2; ++bj) { f32x4 v0 = acc[ai][bj][m][0] * rs, v1 = acc[ai][bj][m][1] * rs;
;                         f32x2 a = gelu_pk((f32x2){v0[0], v0[1]}), b = gelu_pk((f32x2){v0[2], v0[3]}), c = gelu_pk((f32x2){v1[0], v1[1]}), d = gelu_pk((f32x2){v1[2], v1[3]});
;                         u32x4 w; w.x = pkbf(a.x, a.y); w.y = pkbf(b.x, b.y); w.z = pkbf(c.x, c.y); w.w = pkbf(d.x, d.y);
;                         *(u32x4*)(rowp + bj * HALF) = w; } }
	v_and_b32_e32 v9, 0x7fffffff, v5
	v_and_b32_e32 v8, 0x7fffffff, v4
	v_pk_fma_f32 v[8:9], v[8:9], s[36:37], 1.0 op_sel_hi:[1,0,0]
	v_pk_mul_f32 v[12:13], v[12:13], s[58:59] op_sel_hi:[1,0]
	v_rcp_f32_e32 v8, v8
	v_rcp_f32_e32 v9, v9
	v_exp_f32_e32 v12, v12
	v_exp_f32_e32 v13, v13
	v_pk_fma_f32 v[10:11], v[8:9], s[12:13], v[120:121] op_sel_hi:[1,0,0]
	s_nop 0
	v_pk_fma_f32 v[10:11], v[8:9], v[10:11], s[8:9] op_sel_hi:[1,1,0]
	s_nop 0
	v_pk_fma_f32 v[10:11], v[8:9], v[10:11], s[24:25] op_sel_hi:[1,1,0]
	s_nop 0
	v_pk_fma_f32 v[10:11], v[8:9], v[10:11], s[56:57] op_sel_hi:[1,1,0]
	s_nop 0
	v_pk_mul_f32 v[8:9], v[8:9], v[10:11]
	v_pk_mul_f32 v[10:11], v[6:7], v[6:7]
	v_pk_mul_f32 v[8:9], v[12:13], v[8:9]
	s_nop 0
	v_pk_mul_f32 v[12:13], v[4:5], v[8:9]
	v_pk_fma_f32 v[8:9], v[4:5], v[8:9], v[4:5] neg_lo:[1,0,0] neg_hi:[1,0,0]
	v_and_b32_e32 v4, 0x7fffffff, v6
	v_cndmask_b32_e32 v12, v8, v12, vcc
	v_cmp_gt_f32_e32 vcc, 0, v5
	v_and_b32_e32 v5, 0x7fffffff, v7
	v_pk_fma_f32 v[4:5], v[4:5], s[36:37], 1.0 op_sel_hi:[1,0,0]
	v_cndmask_b32_e32 v13, v9, v13, vcc
	v_rcp_f32_e32 v4, v4
	v_rcp_f32_e32 v5, v5
	v_cmp_gt_f32_e32 vcc, 0, v6
	v_pk_fma_f32 v[8:9], v[4:5], s[12:13], v[120:121] op_sel_hi:[1,0,0]
	s_nop 0
	v_pk_fma_f32 v[8:9], v[4:5], v[8:9], s[8:9] op_sel_hi:[1,1,0]
	s_nop 0
	v_pk_fma_f32 v[8:9], v[4:5], v[8:9], s[24:25] op_sel_hi:[1,1,0]
	s_nop 0
	v_pk_fma_f32 v[8:9], v[4:5], v[8:9], s[56:57] op_sel_hi:[1,1,0]
	s_nop 0
	v_pk_mul_f32 v[4:5], v[4:5], v[8:9]
	v_pk_mul_f32 v[8:9], v[10:11], s[58:59] op_sel_hi:[1,0]
	s_nop 0
	v_exp_f32_e32 v8, v8
	v_exp_f32_e32 v9, v9
	s_nop 0
	v_pk_mul_f32 v[4:5], v[8:9], v[4:5]
	s_nop 0
	v_pk_mul_f32 v[8:9], v[6:7], v[4:5]
	v_pk_fma_f32 v[4:5], v[6:7], v[4:5], v[6:7] neg_lo:[1,0,0] neg_hi:[1,0,0]
	s_nop 0
	v_cndmask_b32_e32 v10, v4, v8, vcc
	v_cmp_gt_f32_e32 vcc, 0, v7
	v_and_b32_e32 v4, 0x7fffffff, v0
	s_nop 0
	v_cndmask_b32_e32 v11, v5, v9, vcc
	v_and_b32_e32 v5, 0x7fffffff, v1
	v_pk_fma_f32 v[4:5], v[4:5], s[36:37], 1.0 op_sel_hi:[1,0,0]
	v_pk_mul_f32 v[8:9], v[0:1], v[0:1]
	v_rcp_f32_e32 v4, v4
	v_rcp_f32_e32 v5, v5
	v_pk_mul_f32 v[8:9], v[8:9], s[58:59] op_sel_hi:[1,0]
	v_cmp_gt_f32_e32 vcc, 0, v0
	v_exp_f32_e32 v8, v8
	v_pk_fma_f32 v[6:7], v[4:5], s[12:13], v[120:121] op_sel_hi:[1,0,0]
	v_exp_f32_e32 v9, v9
	v_pk_fma_f32 v[6:7], v[4:5], v[6:7], s[8:9] op_sel_hi:[1,1,0]
	s_nop 0
	v_pk_fma_f32 v[6:7], v[4:5], v[6:7], s[24:25] op_sel_hi:[1,1,0]
	s_nop 0
	v_pk_fma_f32 v[6:7], v[4:5], v[6:7], s[56:57] op_sel_hi:[1,1,0]
	s_nop 0
	v_pk_mul_f32 v[4:5], v[4:5], v[6:7]
	v_pk_mul_f32 v[6:7], v[2:3], v[2:3]
	v_pk_mul_f32 v[4:5], v[8:9], v[4:5]
	s_nop 0
	v_pk_mul_f32 v[8:9], v[0:1], v[4:5]
	v_pk_fma_f32 v[4:5], v[0:1], v[4:5], v[0:1] neg_lo:[1,0,0] neg_hi:[1,0,0]
	v_and_b32_e32 v0, 0x7fffffff, v2
	v_cndmask_b32_e32 v8, v4, v8, vcc
	v_cmp_gt_f32_e32 vcc, 0, v1
	v_and_b32_e32 v1, 0x7fffffff, v3
	v_pk_fma_f32 v[0:1], v[0:1], s[36:37], 1.0 op_sel_hi:[1,0,0]
	v_cndmask_b32_e32 v9, v5, v9, vcc
	v_rcp_f32_e32 v0, v0
	v_rcp_f32_e32 v1, v1
	v_cmp_gt_f32_e32 vcc, 0, v2
	v_pk_fma_f32 v[4:5], v[0:1], s[12:13], v[120:121] op_sel_hi:[1,0,0]
	s_nop 0
	v_pk_fma_f32 v[4:5], v[0:1], v[4:5], s[8:9] op_sel_hi:[1,1,0]
	s_nop 0
	v_pk_fma_f32 v[4:5], v[0:1], v[4:5], s[24:25] op_sel_hi:[1,1,0]
	s_nop 0
	v_pk_fma_f32 v[4:5], v[0:1], v[4:5], s[56:57] op_sel_hi:[1,1,0]
	s_nop 0
	v_pk_mul_f32 v[0:1], v[0:1], v[4:5]
	v_pk_mul_f32 v[4:5], v[6:7], s[58:59] op_sel_hi:[1,0]
	s_nop 0
	v_exp_f32_e32 v4, v4
	v_exp_f32_e32 v5, v5
	s_nop 0
	v_pk_mul_f32 v[0:1], v[4:5], v[0:1]
	s_nop 0
	v_pk_mul_f32 v[4:5], v[2:3], v[0:1]
	v_pk_fma_f32 v[0:1], v[2:3], v[0:1], v[2:3] neg_lo:[1,0,0] neg_hi:[1,0,0]
	v_cvt_pk_bf16_f32 v2, v8, v9
	s_nop 0
	v_cndmask_b32_e32 v4, v0, v4, vcc
	v_cmp_gt_f32_e32 vcc, 0, v3
	v_cvt_pk_bf16_f32 v0, v12, v13
	s_nop 1
	v_cndmask_b32_e32 v3, v1, v5, vcc
	v_cvt_pk_bf16_f32 v1, v10, v11
	v_cvt_pk_bf16_f32 v3, v4, v3
	flat_store_dwordx4 v[16:17], v[0:3] offset:256
	s_andn2_b64 vcc, exec, s[38:39]
	s_mov_b64 s[38:39], -1
	s_cbranch_vccnz .LBB0_135

; __device__ __forceinline__ unsigned pkbf(float lo, float hi) { unsigned r; asm("v_cvt_pk_bf16_f32 %0, %1, %2" : "=v"(r) : "v"(lo), "v"(hi)); return r; }
; __device__ __forceinline__ u32x4 pack8(f32x4 a, f32x4 b) { u32x4 w; w.x = pkbf(a[0], a[1]); w.y = pkbf(a[2], a[3]); w.z = pkbf(b[0], b[1]); w.w = pkbf(b[2], b[3]); return w; }
;     __device__ __forceinline__ void operator()(const f32x4 (&acc)[2][2][4][2], const Unit& u, int wr, int wc, int fr, int fq) const {
;         const int row0 = u.pm * BM + wr * 64 + fr, col0 = u.pn * HALF + wc * 32 + 8 * fq;
; #pragma unroll
;         for (int ai = 0; ai < 2; ++ai)
; #pragma unroll
;             for (int m = 0; m < 4; ++m) { const int row = row0 + ai * HALF + m * 16; const float rs = rinv[row]; f32x4 h[2];
; #pragma unroll
;                 for (int n = 0; n < 2; ++n) { const f32x4 g = acc[ai][0][m][n] * rs, up = acc[ai][1][m][n] * rs;
; #pragma unroll
;                     for (int e = 0; e < 4; ++e) { const float ex = __builtin_amdgcn_exp2f(g[e] * -1.4426950408889634f); h[n][e] = g[e] * __builtin_amdgcn_rcpf(1.0f + ex) * up[e]; } }
;                 *(u32x4*)(H + (size_t)row * ldc + col0) = pack8(h[0], h[1]); }
.LBB0_547:
	v_lshl_add_u32 v138, s78, 8, v145
	v_ashrrev_i32_e32 v139, 31, v138
	v_lshl_add_u64 v[140:141], v[138:139], 2, s[2:3]
	global_load_dword v154, v[140:141], off
	global_load_dword v156, v[140:141], off offset:64
	global_load_dword v158, v[140:141], off offset:128
	global_load_dword v160, v[140:141], off offset:192
	global_load_dword v162, v[140:141], off offset:512
	global_load_dword v164, v[140:141], off offset:576
	global_load_dword v166, v[140:141], off offset:640
	global_load_dword v168, v[140:141], off offset:704
	v_lshl_or_b32 v142, s44, 7, v147
	s_mov_b64 s[78:79], -1
	s_andn2_b64 vcc, exec, s[38:39]
	s_mov_b32 s98, 0xbfb8aa3b
	v_mul_u32_u24_e32 v143, 0x1600, v138
	v_lshl_add_u32 v143, v142, 1, v143
	s_waitcnt vmcnt(0)
	v_pk_mul_f32 v[124:125], v[124:125], v[154:155] op_sel_hi:[1,0]
	v_pk_mul_f32 v[126:127], v[126:127], v[154:155] op_sel_hi:[1,0]
	v_pk_mul_f32 v[116:117], v[116:117], v[154:155] op_sel_hi:[1,0]
	v_pk_mul_f32 v[118:119], v[118:119], v[154:155] op_sel_hi:[1,0]
	v_pk_mul_f32 v[120:121], v[120:121], v[154:155] op_sel_hi:[1,0]
	v_pk_mul_f32 v[122:123], v[122:123], v[154:155] op_sel_hi:[1,0]
	v_pk_mul_f32 v[112:113], v[112:113], v[154:155] op_sel_hi:[1,0]
	v_pk_mul_f32 v[114:115], v[114:115], v[154:155] op_sel_hi:[1,0]
	v_pk_mul_f32 v[186:187], v[124:125], s[98:99] op_sel_hi:[1,0]
	v_pk_mul_f32 v[188:189], v[126:127], s[98:99] op_sel_hi:[1,0]
	v_pk_mul_f32 v[194:195], v[116:117], s[98:99] op_sel_hi:[1,0]
	v_pk_mul_f32 v[196:197], v[118:119], s[98:99] op_sel_hi:[1,0]
	v_exp_f32_e32 v186, v186
	v_exp_f32_e32 v187, v187
	v_exp_f32_e32 v188, v188
	v_exp_f32_e32 v189, v189
	v_exp_f32_e32 v194, v194
	v_exp_f32_e32 v195, v195
	v_exp_f32_e32 v196, v196
	v_exp_f32_e32 v197, v197
	v_pk_add_f32 v[186:187], v[186:187], 1.0 op_sel_hi:[1,0]
	v_pk_add_f32 v[188:189], v[188:189], 1.0 op_sel_hi:[1,0]
	v_pk_add_f32 v[194:195], v[194:195], 1.0 op_sel_hi:[1,0]
	v_pk_add_f32 v[196:197], v[196:197], 1.0 op_sel_hi:[1,0]
	v_rcp_f32_e32 v186, v186
	v_rcp_f32_e32 v187, v187
	v_rcp_f32_e32 v188, v188
	v_rcp_f32_e32 v189, v189
	v_rcp_f32_e32 v194, v194
	v_rcp_f32_e32 v195, v195
	v_rcp_f32_e32 v196, v196
	v_rcp_f32_e32 v197, v197
	v_pk_mul_f32 v[186:187], v[124:125], v[186:187]
	v_pk_mul_f32 v[188:189], v[126:127], v[188:189]
	v_pk_mul_f32 v[194:195], v[116:117], v[194:195]
	v_pk_mul_f32 v[196:197], v[118:119], v[196:197]
	v_pk_mul_f32 v[186:187], v[120:121], v[186:187]
	v_pk_mul_f32 v[188:189], v[122:123], v[188:189]
	v_pk_mul_f32 v[194:195], v[112:113], v[194:195]
	v_pk_mul_f32 v[196:197], v[114:115], v[196:197]
	v_cvt_pk_bf16_f32 v170, v186, v187
	v_cvt_pk_bf16_f32 v171, v188, v189
	v_cvt_pk_bf16_f32 v172, v194, v195
	v_cvt_pk_bf16_f32 v173, v196, v197
	global_store_dwordx4 v143, v[170:173], s[40:41]
	v_pk_mul_f32 v[108:109], v[108:109], v[156:157] op_sel_hi:[1,0]
	v_pk_mul_f32 v[110:111], v[110:111], v[156:157] op_sel_hi:[1,0]
	v_pk_mul_f32 v[100:101], v[100:101], v[156:157] op_sel_hi:[1,0]
	v_pk_mul_f32 v[102:103], v[102:103], v[156:157] op_sel_hi:[1,0]
	v_pk_mul_f32 v[104:105], v[104:105], v[156:157] op_sel_hi:[1,0]
	v_pk_mul_f32 v[106:107], v[106:107], v[156:157] op_sel_hi:[1,0]
	v_pk_mul_f32 v[96:97], v[96:97], v[156:157] op_sel_hi:[1,0]
	v_pk_mul_f32 v[98:99], v[98:99], v[156:157] op_sel_hi:[1,0]
	v_pk_mul_f32 v[186:187], v[108:109], s[98:99] op_sel_hi:[1,0]
	v_pk_mul_f32 v[188:189], v[110:111], s[98:99] op_sel_hi:[1,0]
	v_pk_mul_f32 v[194:195], v[100:101], s[98:99] op_sel_hi:[1,0]
	v_pk_mul_f32 v[196:197], v[102:103], s[98:99] op_sel_hi:[1,0]
	v_exp_f32_e32 v186, v186
	v_exp_f32_e32 v187, v187
	v_exp_f32_e32 v188, v188
	v_exp_f32_e32 v189, v189
	v_exp_f32_e32 v194, v194
	v_exp_f32_e32 v195, v195
	v_exp_f32_e32 v196, v196
	v_exp_f32_e32 v197, v197
	v_pk_add_f32 v[186:187], v[186:187], 1.0 op_sel_hi:[1,0]
	v_pk_add_f32 v[188:189], v[188:189], 1.0 op_sel_hi:[1,0]
	v_pk_add_f32 v[194:195], v[194:195], 1.0 op_sel_hi:[1,0]
	v_pk_add_f32 v[196:197], v[196:197], 1.0 op_sel_hi:[1,0]
	v_rcp_f32_e32 v186, v186
	v_rcp_f32_e32 v187, v187
	v_rcp_f32_e32 v188, v188
	v_rcp_f32_e32 v189, v189
	v_rcp_f32_e32 v194, v194
	v_rcp_f32_e32 v195, v195
	v_rcp_f32_e32 v196, v196
	v_rcp_f32_e32 v197, v197
	v_pk_mul_f32 v[186:187], v[108:109], v[186:187]
	v_pk_mul_f32 v[188:189], v[110:111], v[188:189]
	v_pk_mul_f32 v[194:195], v[100:101], v[194:195]
	v_pk_mul_f32 v[196:197], v[102:103], v[196:197]
	v_pk_mul_f32 v[186:187], v[104:105], v[186:187]
	v_pk_mul_f32 v[188:189], v[106:107], v[188:189]
	v_pk_mul_f32 v[194:195], v[96:97], v[194:195]
	v_pk_mul_f32 v[196:197], v[98:99], v[196:197]
	v_cvt_pk_bf16_f32 v174, v186, v187
	v_cvt_pk_bf16_f32 v175, v188, v189
	v_cvt_pk_bf16_f32 v176, v194, v195
	v_cvt_pk_bf16_f32 v177, v196, v197
	v_add_u32_e32 v150, 0x16000, v143
	global_store_dwordx4 v150, v[174:177], s[40:41]
	v_pk_mul_f32 v[92:93], v[92:93], v[158:159] op_sel_hi:[1,0]
	v_pk_mul_f32 v[94:95], v[94:95], v[158:159] op_sel_hi:[1,0]
	v_pk_mul_f32 v[84:85], v[84:85], v[158:159] op_sel_hi:[1,0]
	v_pk_mul_f32 v[86:87], v[86:87], v[158:159] op_sel_hi:[1,0]
	v_pk_mul_f32 v[88:89], v[88:89], v[158:159] op_sel_hi:[1,0]
	v_pk_mul_f32 v[90:91], v[90:91], v[158:159] op_sel_hi:[1,0]
	v_pk_mul_f32 v[80:81], v[80:81], v[158:159] op_sel_hi:[1,0]
	v_pk_mul_f32 v[82:83], v[82:83], v[158:159] op_sel_hi:[1,0]
	v_pk_mul_f32 v[186:187], v[92:93], s[98:99] op_sel_hi:[1,0]
	v_pk_mul_f32 v[188:189], v[94:95], s[98:99] op_sel_hi:[1,0]
	v_pk_mul_f32 v[194:195], v[84:85], s[98:99] op_sel_hi:[1,0]
	v_pk_mul_f32 v[196:197], v[86:87], s[98:99] op_sel_hi:[1,0]
	v_exp_f32_e32 v186, v186
	v_exp_f32_e32 v187, v187
	v_exp_f32_e32 v188, v188
	v_exp_f32_e32 v189, v189
	v_exp_f32_e32 v194, v194
; __device__ __forceinline__ u32x4 pack8(f32x4 a, f32x4 b) { u32x4 w; w.x = pkbf(a[0], a[1]); w.y = pkbf(a[2], a[3]); w.z = pkbf(b[0], b[1]); w.w = pkbf(b[2], b[3]); return w; }
;     __device__ __forceinline__ void operator()(const f32x4 (&acc)[2][2][4][2], const Unit& u, int wr, int wc, int fr, int fq) const {
;     ...
;             for (int m = 0; m < 4; ++m) { const int row = row0 + ai * HALF + m * 16; const float rs = rinv[row]; f32x4 h[2];
; #pragma unroll
;                 for (int n = 0; n < 2; ++n) { const f32x4 g = acc[ai][0][m][n] * rs, up = acc[ai][1][m][n] * rs;
; #pragma unroll
;                     for (int e = 0; e < 4; ++e) { const float ex = __builtin_amdgcn_exp2f(g[e] * -1.4426950408889634f); h[n][e] = g[e] * __builtin_amdgcn_rcpf(1.0f + ex) * up[e]; } }
;                 *(u32x4*)(H + (size_t)row * ldc + col0) = pack8(h[0], h[1]); }
	v_exp_f32_e32 v195, v195
	v_exp_f32_e32 v196, v196
	v_exp_f32_e32 v197, v197
	v_pk_add_f32 v[186:187], v[186:187], 1.0 op_sel_hi:[1,0]
	v_pk_add_f32 v[188:189], v[188:189], 1.0 op_sel_hi:[1,0]
	v_pk_add_f32 v[194:195], v[194:195], 1.0 op_sel_hi:[1,0]
	v_pk_add_f32 v[196:197], v[196:197], 1.0 op_sel_hi:[1,0]
	v_rcp_f32_e32 v186, v186
	v_rcp_f32_e32 v187, v187
	v_rcp_f32_e32 v188, v188
	v_rcp_f32_e32 v189, v189
	v_rcp_f32_e32 v194, v194
	v_rcp_f32_e32 v195, v195
	v_rcp_f32_e32 v196, v196
	v_rcp_f32_e32 v197, v197
	v_pk_mul_f32 v[186:187], v[92:93], v[186:187]
	v_pk_mul_f32 v[188:189], v[94:95], v[188:189]
	v_pk_mul_f32 v[194:195], v[84:85], v[194:195]
	v_pk_mul_f32 v[196:197], v[86:87], v[196:197]
	v_pk_mul_f32 v[186:187], v[88:89], v[186:187]
	v_pk_mul_f32 v[188:189], v[90:91], v[188:189]
	v_pk_mul_f32 v[194:195], v[80:81], v[194:195]
	v_pk_mul_f32 v[196:197], v[82:83], v[196:197]
	v_cvt_pk_bf16_f32 v178, v186, v187
	v_cvt_pk_bf16_f32 v179, v188, v189
	v_cvt_pk_bf16_f32 v180, v194, v195
	v_cvt_pk_bf16_f32 v181, v196, v197
	v_add_u32_e32 v150, 0x2c000, v143
	global_store_dwordx4 v150, v[178:181], s[40:41]
	v_pk_mul_f32 v[76:77], v[76:77], v[160:161] op_sel_hi:[1,0]
	v_pk_mul_f32 v[78:79], v[78:79], v[160:161] op_sel_hi:[1,0]
	v_pk_mul_f32 v[68:69], v[68:69], v[160:161] op_sel_hi:[1,0]
	v_pk_mul_f32 v[70:71], v[70:71], v[160:161] op_sel_hi:[1,0]
	v_pk_mul_f32 v[72:73], v[72:73], v[160:161] op_sel_hi:[1,0]
	v_pk_mul_f32 v[74:75], v[74:75], v[160:161] op_sel_hi:[1,0]
	v_pk_mul_f32 v[64:65], v[64:65], v[160:161] op_sel_hi:[1,0]
	v_pk_mul_f32 v[66:67], v[66:67], v[160:161] op_sel_hi:[1,0]
	v_pk_mul_f32 v[186:187], v[76:77], s[98:99] op_sel_hi:[1,0]
	v_pk_mul_f32 v[188:189], v[78:79], s[98:99] op_sel_hi:[1,0]
	v_pk_mul_f32 v[194:195], v[68:69], s[98:99] op_sel_hi:[1,0]
	v_pk_mul_f32 v[196:197], v[70:71], s[98:99] op_sel_hi:[1,0]
	v_exp_f32_e32 v186, v186
	v_exp_f32_e32 v187, v187
	v_exp_f32_e32 v188, v188
	v_exp_f32_e32 v189, v189
	v_exp_f32_e32 v194, v194
	v_exp_f32_e32 v195, v195
	v_exp_f32_e32 v196, v196
	v_exp_f32_e32 v197, v197
	v_pk_add_f32 v[186:187], v[186:187], 1.0 op_sel_hi:[1,0]
	v_pk_add_f32 v[188:189], v[188:189], 1.0 op_sel_hi:[1,0]
	v_pk_add_f32 v[194:195], v[194:195], 1.0 op_sel_hi:[1,0]
	v_pk_add_f32 v[196:197], v[196:197], 1.0 op_sel_hi:[1,0]
	v_rcp_f32_e32 v186, v186
	v_rcp_f32_e32 v187, v187
	v_rcp_f32_e32 v188, v188
	v_rcp_f32_e32 v189, v189
	v_rcp_f32_e32 v194, v194
	v_rcp_f32_e32 v195, v195
	v_rcp_f32_e32 v196, v196
	v_rcp_f32_e32 v197, v197
	v_pk_mul_f32 v[186:187], v[76:77], v[186:187]
	v_pk_mul_f32 v[188:189], v[78:79], v[188:189]
	v_pk_mul_f32 v[194:195], v[68:69], v[194:195]
	v_pk_mul_f32 v[196:197], v[70:71], v[196:197]
	v_pk_mul_f32 v[186:187], v[72:73], v[186:187]
	v_pk_mul_f32 v[188:189], v[74:75], v[188:189]
	v_pk_mul_f32 v[194:195], v[64:65], v[194:195]
	v_pk_mul_f32 v[196:197], v[66:67], v[196:197]
	v_cvt_pk_bf16_f32 v182, v186, v187
	v_cvt_pk_bf16_f32 v183, v188, v189
	v_cvt_pk_bf16_f32 v184, v194, v195
	v_cvt_pk_bf16_f32 v185, v196, v197
	v_add_u32_e32 v150, 0x42000, v143
	global_store_dwordx4 v150, v[182:185], s[40:41]
	v_pk_mul_f32 v[60:61], v[60:61], v[162:163] op_sel_hi:[1,0]
	v_pk_mul_f32 v[62:63], v[62:63], v[162:163] op_sel_hi:[1,0]
	v_pk_mul_f32 v[52:53], v[52:53], v[162:163] op_sel_hi:[1,0]
	v_pk_mul_f32 v[54:55], v[54:55], v[162:163] op_sel_hi:[1,0]
	v_pk_mul_f32 v[56:57], v[56:57], v[162:163] op_sel_hi:[1,0]
	v_pk_mul_f32 v[58:59], v[58:59], v[162:163] op_sel_hi:[1,0]
	v_pk_mul_f32 v[48:49], v[48:49], v[162:163] op_sel_hi:[1,0]
	v_pk_mul_f32 v[50:51], v[50:51], v[162:163] op_sel_hi:[1,0]
	v_pk_mul_f32 v[186:187], v[60:61], s[98:99] op_sel_hi:[1,0]
	v_pk_mul_f32 v[188:189], v[62:63], s[98:99] op_sel_hi:[1,0]
	v_pk_mul_f32 v[194:195], v[52:53], s[98:99] op_sel_hi:[1,0]
	v_pk_mul_f32 v[196:197], v[54:55], s[98:99] op_sel_hi:[1,0]
	v_exp_f32_e32 v186, v186
	v_exp_f32_e32 v187, v187
	v_exp_f32_e32 v188, v188
	v_exp_f32_e32 v189, v189
	v_exp_f32_e32 v194, v194
	v_exp_f32_e32 v195, v195
	v_exp_f32_e32 v196, v196
	v_exp_f32_e32 v197, v197
	v_pk_add_f32 v[186:187], v[186:187], 1.0 op_sel_hi:[1,0]
	v_pk_add_f32 v[188:189], v[188:189], 1.0 op_sel_hi:[1,0]
	v_pk_add_f32 v[194:195], v[194:195], 1.0 op_sel_hi:[1,0]
	v_pk_add_f32 v[196:197], v[196:197], 1.0 op_sel_hi:[1,0]
	v_rcp_f32_e32 v186, v186
	v_rcp_f32_e32 v187, v187
	v_rcp_f32_e32 v188, v188
	v_rcp_f32_e32 v189, v189
	v_rcp_f32_e32 v194, v194
	v_rcp_f32_e32 v195, v195
	v_rcp_f32_e32 v196, v196
	v_rcp_f32_e32 v197, v197
	v_pk_mul_f32 v[186:187], v[60:61], v[186:187]
	v_pk_mul_f32 v[188:189], v[62:63], v[188:189]
	v_pk_mul_f32 v[194:195], v[52:53], v[194:195]
	v_pk_mul_f32 v[196:197], v[54:55], v[196:197]
	v_pk_mul_f32 v[186:187], v[56:57], v[186:187]
	v_pk_mul_f32 v[188:189], v[58:59], v[188:189]
	v_pk_mul_f32 v[194:195], v[48:49], v[194:195]
	v_pk_mul_f32 v[196:197], v[50:51], v[196:197]
	v_cvt_pk_bf16_f32 v170, v186, v187
	v_cvt_pk_bf16_f32 v171, v188, v189
	v_cvt_pk_bf16_f32 v172, v194, v195
	v_cvt_pk_bf16_f32 v173, v196, v197
	v_add_u32_e32 v150, 0xb0000, v143
	global_store_dwordx4 v150, v[170:173], s[40:41]
	v_pk_mul_f32 v[44:45], v[44:45], v[164:165] op_sel_hi:[1,0]
	v_pk_mul_f32 v[46:47], v[46:47], v[164:165] op_sel_hi:[1,0]
	v_pk_mul_f32 v[36:37], v[36:37], v[164:165] op_sel_hi:[1,0]
	v_pk_mul_f32 v[38:39], v[38:39], v[164:165] op_sel_hi:[1,0]
	v_pk_mul_f32 v[40:41], v[40:41], v[164:165] op_sel_hi:[1,0]
	v_pk_mul_f32 v[42:43], v[42:43], v[164:165] op_sel_hi:[1,0]
	v_pk_mul_f32 v[32:33], v[32:33], v[164:165] op_sel_hi:[1,0]
	v_pk_mul_f32 v[34:35], v[34:35], v[164:165] op_sel_hi:[1,0]
; __device__ __forceinline__ u32x4 pack8(f32x4 a, f32x4 b) { u32x4 w; w.x = pkbf(a[0], a[1]); w.y = pkbf(a[2], a[3]); w.z = pkbf(b[0], b[1]); w.w = pkbf(b[2], b[3]); return w; }
;     __device__ __forceinline__ void operator()(const f32x4 (&acc)[2][2][4][2], const Unit& u, int wr, int wc, int fr, int fq) const {
;     ...
;             for (int m = 0; m < 4; ++m) { const int row = row0 + ai * HALF + m * 16; const float rs = rinv[row]; f32x4 h[2];
; #pragma unroll
;                 for (int n = 0; n < 2; ++n) { const f32x4 g = acc[ai][0][m][n] * rs, up = acc[ai][1][m][n] * rs;
; #pragma unroll
;                     for (int e = 0; e < 4; ++e) { const float ex = __builtin_amdgcn_exp2f(g[e] * -1.4426950408889634f); h[n][e] = g[e] * __builtin_amdgcn_rcpf(1.0f + ex) * up[e]; } }
;                 *(u32x4*)(H + (size_t)row * ldc + col0) = pack8(h[0], h[1]); }
	v_pk_mul_f32 v[186:187], v[44:45], s[98:99] op_sel_hi:[1,0]
	v_pk_mul_f32 v[188:189], v[46:47], s[98:99] op_sel_hi:[1,0]
	v_pk_mul_f32 v[194:195], v[36:37], s[98:99] op_sel_hi:[1,0]
	v_pk_mul_f32 v[196:197], v[38:39], s[98:99] op_sel_hi:[1,0]
	v_exp_f32_e32 v186, v186
	v_exp_f32_e32 v187, v187
	v_exp_f32_e32 v188, v188
	v_exp_f32_e32 v189, v189
	v_exp_f32_e32 v194, v194
	v_exp_f32_e32 v195, v195
	v_exp_f32_e32 v196, v196
	v_exp_f32_e32 v197, v197
	v_pk_add_f32 v[186:187], v[186:187], 1.0 op_sel_hi:[1,0]
	v_pk_add_f32 v[188:189], v[188:189], 1.0 op_sel_hi:[1,0]
	v_pk_add_f32 v[194:195], v[194:195], 1.0 op_sel_hi:[1,0]
	v_pk_add_f32 v[196:197], v[196:197], 1.0 op_sel_hi:[1,0]
	v_rcp_f32_e32 v186, v186
	v_rcp_f32_e32 v187, v187
	v_rcp_f32_e32 v188, v188
	v_rcp_f32_e32 v189, v189
	v_rcp_f32_e32 v194, v194
	v_rcp_f32_e32 v195, v195
	v_rcp_f32_e32 v196, v196
	v_rcp_f32_e32 v197, v197
	v_pk_mul_f32 v[186:187], v[44:45], v[186:187]
	v_pk_mul_f32 v[188:189], v[46:47], v[188:189]
	v_pk_mul_f32 v[194:195], v[36:37], v[194:195]
	v_pk_mul_f32 v[196:197], v[38:39], v[196:197]
	v_pk_mul_f32 v[186:187], v[40:41], v[186:187]
	v_pk_mul_f32 v[188:189], v[42:43], v[188:189]
	v_pk_mul_f32 v[194:195], v[32:33], v[194:195]
	v_pk_mul_f32 v[196:197], v[34:35], v[196:197]
	v_cvt_pk_bf16_f32 v174, v186, v187
	v_cvt_pk_bf16_f32 v175, v188, v189
	v_cvt_pk_bf16_f32 v176, v194, v195
	v_cvt_pk_bf16_f32 v177, v196, v197
	v_add_u32_e32 v150, 0xc6000, v143
	global_store_dwordx4 v150, v[174:177], s[40:41]
	v_pk_mul_f32 v[28:29], v[28:29], v[166:167] op_sel_hi:[1,0]
	v_pk_mul_f32 v[30:31], v[30:31], v[166:167] op_sel_hi:[1,0]
	v_pk_mul_f32 v[20:21], v[20:21], v[166:167] op_sel_hi:[1,0]
	v_pk_mul_f32 v[22:23], v[22:23], v[166:167] op_sel_hi:[1,0]
	v_pk_mul_f32 v[24:25], v[24:25], v[166:167] op_sel_hi:[1,0]
	v_pk_mul_f32 v[26:27], v[26:27], v[166:167] op_sel_hi:[1,0]
	v_pk_mul_f32 v[16:17], v[16:17], v[166:167] op_sel_hi:[1,0]
	v_pk_mul_f32 v[18:19], v[18:19], v[166:167] op_sel_hi:[1,0]
	v_pk_mul_f32 v[186:187], v[28:29], s[98:99] op_sel_hi:[1,0]
	v_pk_mul_f32 v[188:189], v[30:31], s[98:99] op_sel_hi:[1,0]
	v_pk_mul_f32 v[194:195], v[20:21], s[98:99] op_sel_hi:[1,0]
	v_pk_mul_f32 v[196:197], v[22:23], s[98:99] op_sel_hi:[1,0]
	v_exp_f32_e32 v186, v186
	v_exp_f32_e32 v187, v187
	v_exp_f32_e32 v188, v188
	v_exp_f32_e32 v189, v189
	v_exp_f32_e32 v194, v194
	v_exp_f32_e32 v195, v195
	v_exp_f32_e32 v196, v196
	v_exp_f32_e32 v197, v197
	v_pk_add_f32 v[186:187], v[186:187], 1.0 op_sel_hi:[1,0]
	v_pk_add_f32 v[188:189], v[188:189], 1.0 op_sel_hi:[1,0]
	v_pk_add_f32 v[194:195], v[194:195], 1.0 op_sel_hi:[1,0]
	v_pk_add_f32 v[196:197], v[196:197], 1.0 op_sel_hi:[1,0]
	v_rcp_f32_e32 v186, v186
	v_rcp_f32_e32 v187, v187
	v_rcp_f32_e32 v188, v188
	v_rcp_f32_e32 v189, v189
	v_rcp_f32_e32 v194, v194
	v_rcp_f32_e32 v195, v195
	v_rcp_f32_e32 v196, v196
	v_rcp_f32_e32 v197, v197
	v_pk_mul_f32 v[186:187], v[28:29], v[186:187]
	v_pk_mul_f32 v[188:189], v[30:31], v[188:189]
	v_pk_mul_f32 v[194:195], v[20:21], v[194:195]
	v_pk_mul_f32 v[196:197], v[22:23], v[196:197]
	v_pk_mul_f32 v[186:187], v[24:25], v[186:187]
	v_pk_mul_f32 v[188:189], v[26:27], v[188:189]
	v_pk_mul_f32 v[194:195], v[16:17], v[194:195]
	v_pk_mul_f32 v[196:197], v[18:19], v[196:197]
	v_cvt_pk_bf16_f32 v178, v186, v187
	v_cvt_pk_bf16_f32 v179, v188, v189
	v_cvt_pk_bf16_f32 v180, v194, v195
	v_cvt_pk_bf16_f32 v181, v196, v197
	v_add_u32_e32 v150, 0xdc000, v143
	global_store_dwordx4 v150, v[178:181], s[40:41]
	v_pk_mul_f32 v[12:13], v[12:13], v[168:169] op_sel_hi:[1,0]
	v_pk_mul_f32 v[14:15], v[14:15], v[168:169] op_sel_hi:[1,0]
	v_pk_mul_f32 v[4:5], v[4:5], v[168:169] op_sel_hi:[1,0]
	v_pk_mul_f32 v[6:7], v[6:7], v[168:169] op_sel_hi:[1,0]
	v_pk_mul_f32 v[8:9], v[8:9], v[168:169] op_sel_hi:[1,0]
	v_pk_mul_f32 v[10:11], v[10:11], v[168:169] op_sel_hi:[1,0]
	v_pk_mul_f32 v[0:1], v[0:1], v[168:169] op_sel_hi:[1,0]
	v_pk_mul_f32 v[2:3], v[2:3], v[168:169] op_sel_hi:[1,0]
	v_pk_mul_f32 v[186:187], v[12:13], s[98:99] op_sel_hi:[1,0]
	v_pk_mul_f32 v[188:189], v[14:15], s[98:99] op_sel_hi:[1,0]
	v_pk_mul_f32 v[194:195], v[4:5], s[98:99] op_sel_hi:[1,0]
	v_pk_mul_f32 v[196:197], v[6:7], s[98:99] op_sel_hi:[1,0]
	v_exp_f32_e32 v186, v186
	v_exp_f32_e32 v187, v187
	v_exp_f32_e32 v188, v188
	v_exp_f32_e32 v189, v189
	v_exp_f32_e32 v194, v194
	v_exp_f32_e32 v195, v195
	v_exp_f32_e32 v196, v196
	v_exp_f32_e32 v197, v197
	v_pk_add_f32 v[186:187], v[186:187], 1.0 op_sel_hi:[1,0]
	v_pk_add_f32 v[188:189], v[188:189], 1.0 op_sel_hi:[1,0]
	v_pk_add_f32 v[194:195], v[194:195], 1.0 op_sel_hi:[1,0]
	v_pk_add_f32 v[196:197], v[196:197], 1.0 op_sel_hi:[1,0]
	v_rcp_f32_e32 v186, v186
	v_rcp_f32_e32 v187, v187
	v_rcp_f32_e32 v188, v188
	v_rcp_f32_e32 v189, v189
	v_rcp_f32_e32 v194, v194
	v_rcp_f32_e32 v195, v195
	v_rcp_f32_e32 v196, v196
	v_rcp_f32_e32 v197, v197
	v_pk_mul_f32 v[186:187], v[12:13], v[186:187]
	v_pk_mul_f32 v[188:189], v[14:15], v[188:189]
	v_pk_mul_f32 v[194:195], v[4:5], v[194:195]
	v_pk_mul_f32 v[196:197], v[6:7], v[196:197]
	v_pk_mul_f32 v[186:187], v[8:9], v[186:187]
	v_pk_mul_f32 v[188:189], v[10:11], v[188:189]
	v_pk_mul_f32 v[194:195], v[0:1], v[194:195]
	v_pk_mul_f32 v[196:197], v[2:3], v[196:197]
	v_cvt_pk_bf16_f32 v182, v186, v187
	v_cvt_pk_bf16_f32 v183, v188, v189
	v_cvt_pk_bf16_f32 v184, v194, v195
	v_cvt_pk_bf16_f32 v185, v196, v197
	v_add_u32_e32 v150, 0xf2000, v143
	global_store_dwordx4 v150, v[182:185], s[40:41]
	s_cbranch_vccnz .LBB0_540
	s_andn2_b64 vcc, exec, s[0:1]
	s_cbranch_vccnz .LBB0_539
	s_barrier
	s_branch .LBB0_539
